# v064 + cache hints: merge-phase and down-proj outputs stored without nt (consumed by the next phase), first RMSNorm input loads nt
# baseline (speedup 1.0000x reference)
; __device__ __forceinline__ unsigned pk2(float lo, float hi) { return f2bf(lo) | (f2bf(hi) << 16); }
; __global__ void __launch_bounds__(NWAVES * 64, 2) hybrid_fwd(Args a) {
;     ...
;         {
;             const f32x4* gr = (const f32x4*)a.g_attn + lane; f32x4 gg[4];
; #pragma unroll
;             for (int j = 0; j < 4; ++j) gg[j] = gr[64 * j];
;             for (int m0 = gw * 4; m0 < M; m0 += NGW * 4) {
;                 f32x4 v[4][4]; float s2[4];
; #pragma unroll
;                 for (int q = 0; q < 4; ++q) { const f32x4* xr = (const f32x4*)(a.x + (size_t)(m0 + q) * D) + lane;
; #pragma unroll
;                     for (int j = 0; j < 4; ++j) v[q][j] = __builtin_nontemporal_load(xr + 64 * j); }
; #pragma unroll
;                 for (int q = 0; q < 4; ++q) { s2[q] = 0.f;
; #pragma unroll
;                     for (int j = 0; j < 4; ++j) s2[q] += (v[q][j].x * v[q][j].x + v[q][j].y * v[q][j].y) + (v[q][j].z * v[q][j].z + v[q][j].w * v[q][j].w); }
; #pragma unroll
;                 for (int q = 0; q < 4; ++q) { const float rstd = __builtin_amdgcn_rsqf(wave_sum(s2[q]) * (1.f / D) + RMS_EPS);
;                     unsigned long long* o8 = (unsigned long long*)(XN + (size_t)(m0 + q) * D) + lane;
; #pragma unroll
;                     for (int j = 0; j < 4; ++j) { const f32x4 y = v[q][j] * rstd * gg[j];
;                         o8[64 * j] = (unsigned long long)pk2(y.x, y.y) | ((unsigned long long)pk2(y.z, y.w) << 32); } }
.LBB0_90:
	s_or_b64 exec, exec, s[2:3]
	s_lshl_b32 s14, s33, 5
	s_cmpk_lt_i32 s0, 0x4000
	s_cbranch_scc0 .LBB0_93
	v_lshlrev_b32_e32 v18, 4, v21
	global_load_dwordx4 v[0:3], v18, s[60:61] nt
	global_load_dwordx4 v[4:7], v18, s[60:61] offset:1024 nt
	global_load_dwordx4 v[8:11], v18, s[60:61] offset:2048 nt
	global_load_dwordx4 v[12:15], v18, s[60:61] offset:3072 nt
	s_lshl_b32 s4, s0, 2
	s_ashr_i32 s5, s4, 31
	s_lshl_b64 s[0:1], s[4:5], 11
	v_mov_b32_e32 v19, 0
	s_add_u32 s0, s74, s0
	v_mov_b32_e32 v17, v19
	s_addc_u32 s1, s75, s1
	v_lshl_add_u64 v[16:17], s[0:1], 0, v[16:17]
	s_mov_b64 s[0:1], 0x3000000
	s_ashr_i32 s15, s14, 31
	v_lshl_add_u64 v[48:49], v[16:17], 0, s[0:1]
	s_lshl_b64 s[6:7], s[14:15], 11
	s_lshl_b64 s[0:1], s[4:5], 12
	s_add_u32 s0, s56, s0
	s_addc_u32 s1, s57, s1
	v_lshl_add_u64 v[50:51], s[0:1], 0, v[18:19]
	s_lshl_b64 s[8:9], s[14:15], 12
	s_movk_i32 s0, 0x1000
	v_mov_b32_e32 v54, 0x358637bd
	s_movk_i32 s1, 0x7fff
	s_mov_b32 s5, 0xffff0000

; __device__ __forceinline__ float bf_lo(unsigned w) { return __uint_as_float(w << 16); }
; __device__ __forceinline__ float bf_hi(unsigned w) { return __uint_as_float(w & 0xffff0000u); }
; __device__ __forceinline__ u32x4 pack8(const f32x4 a, const f32x4 b) { u32x4 w; w.x = cvt_pk_bf16(a[0], a[1]); w.y = cvt_pk_bf16(a[2], a[3]); w.z = cvt_pk_bf16(b[0], b[1]); w.w = cvt_pk_bf16(b[2], b[3]); return w; }
;     __device__ __forceinline__ void operator()(const f32x4 (&acc)[2][2][4][2], const Unit& u, int wr, int wc, int fr, int fq) const {
;         const int row0 = u.pm * BM + wr * 64 + fr, col0 = u.pn * BM + wc * 32 + 8 * fq;
;         f32x4 ps[2][2];
; #pragma unroll
;         for (int bj = 0; bj < 2; ++bj) { ps[bj][0] = *(const f32x4*)(pscale + col0 + bj * HALF); ps[bj][1] = *(const f32x4*)(pscale + col0 + bj * HALF + 4); }
; #pragma unroll
;         for (int ai = 0; ai < 2; ++ai)
; #pragma unroll
;             for (int m = 0; m < 4; ++m) {
;                 const size_t row = (size_t)(row0 + ai * HALF + m * 16);
; #pragma unroll
;                 for (int bj = 0; bj < 2; ++bj) {
;                     const int c = col0 + bj * HALF;
;                     const u32x4 a8 = __builtin_nontemporal_load((const u32x4*)(A + row * 1024 + c)), ga = __builtin_nontemporal_load((const u32x4*)(G + row * 2048 + c)), gp = __builtin_nontemporal_load((const u32x4*)(G + row * 2048 + 1024 + c));
;                     const f32x4 y0 = acc[ai][bj][m][0] * ps[bj][0], y1 = acc[ai][bj][m][1] * ps[bj][1];
;                     f32x4 o0, o1;
;                     o0[0] = bf_lo(ga.x) * bf_lo(a8.x) + bf_lo(gp.x) * y0[0]; o0[1] = bf_hi(ga.x) * bf_hi(a8.x) + bf_hi(gp.x) * y0[1];
;                     o0[2] = bf_lo(ga.y) * bf_lo(a8.y) + bf_lo(gp.y) * y0[2]; o0[3] = bf_hi(ga.y) * bf_hi(a8.y) + bf_hi(gp.y) * y0[3];
;                     o1[0] = bf_lo(ga.z) * bf_lo(a8.z) + bf_lo(gp.z) * y1[0]; o1[1] = bf_hi(ga.z) * bf_hi(a8.z) + bf_hi(gp.z) * y1[1];
;                     o1[2] = bf_lo(ga.w) * bf_lo(a8.w) + bf_lo(gp.w) * y1[2]; o1[3] = bf_hi(ga.w) * bf_hi(a8.w) + bf_hi(gp.w) * y1[3];
;                     __builtin_nontemporal_store(pack8(o0, o1), (u32x4*)(Mg + row * 1024 + c));
.LBB0_381:
	v_lshl_add_u32 v158, s22, 8, v160
	v_lshl_or_b32 v8, s39, 8, v162
	v_ashrrev_i32_e32 v159, 31, v158
	v_ashrrev_i32_e32 v9, 31, v8
	v_lshlrev_b64 v[152:153], 11, v[158:159]
	v_lshl_add_u64 v[12:13], v[8:9], 2, s[44:45]
	v_lshl_add_u64 v[14:15], s[46:47], 0, v[152:153]
	v_lshlrev_b64 v[156:157], 1, v[8:9]
	global_load_dwordx4 v[24:27], v[12:13], off offset:16
	global_load_dwordx4 v[28:31], v[12:13], off
	v_lshlrev_b64 v[10:11], 12, v[158:159]
	v_lshl_add_u64 v[178:179], v[14:15], 0, v[156:157]
	global_load_dwordx4 v[166:169], v[178:179], off nt
	v_lshl_add_u64 v[8:9], s[62:63], 0, v[10:11]
	v_lshl_add_u64 v[180:181], v[8:9], 0, v[156:157]
	global_load_dwordx4 v[170:173], v[180:181], off offset:2048 nt
	global_load_dwordx4 v[174:177], v[180:181], off nt
	global_load_dwordx4 v[8:11], v[12:13], off offset:528
	s_nop 0
	global_load_dwordx4 v[12:15], v[12:13], off offset:512
	s_andn2_b64 vcc, exec, s[2:3]
	s_mov_b64 s[2:3], -1
	s_waitcnt vmcnt(0)
	v_pk_mul_f32 v[138:139], v[138:139], v[26:27]
	v_pk_mul_f32 v[142:143], v[142:143], v[30:31]
	v_pk_mul_f32 v[140:141], v[140:141], v[28:29]
	v_pk_mul_f32 v[136:137], v[136:137], v[24:25]
	v_mov_b32_e32 v183, v140
	v_mov_b32_e32 v185, v142
	v_mov_b32_e32 v187, v136
	v_mov_b32_e32 v189, v138
	v_lshlrev_b32_e32 v182, 16, v166
	v_lshlrev_b32_e32 v193, 16, v170
	v_and_b32_e32 v140, 0xffff0000, v166
	v_and_b32_e32 v195, 0xffff0000, v170
	v_and_b32_e32 v194, 0xffff0000, v174
	v_lshlrev_b32_e32 v184, 16, v167
	v_lshlrev_b32_e32 v197, 16, v171
	v_lshlrev_b32_e32 v196, 16, v175
	v_and_b32_e32 v142, 0xffff0000, v167
	v_and_b32_e32 v167, 0xffff0000, v171
	v_and_b32_e32 v166, 0xffff0000, v175
	v_lshlrev_b32_e32 v186, 16, v168
	v_lshlrev_b32_e32 v171, 16, v172
	v_lshlrev_b32_e32 v170, 16, v176
	v_and_b32_e32 v136, 0xffff0000, v168
	v_lshlrev_b32_e32 v188, 16, v169
	v_and_b32_e32 v138, 0xffff0000, v169
	v_and_b32_e32 v169, 0xffff0000, v173
	v_and_b32_e32 v168, 0xffff0000, v177
	v_lshlrev_b32_e32 v192, 16, v174
	v_and_b32_e32 v175, 0xffff0000, v172
	v_and_b32_e32 v174, 0xffff0000, v176
	v_lshlrev_b32_e32 v199, 16, v173
	v_lshlrev_b32_e32 v198, 16, v177
	v_pk_mul_f32 v[140:141], v[140:141], v[194:195]
	v_pk_mul_f32 v[176:177], v[184:185], v[196:197]
	v_pk_mul_f32 v[142:143], v[142:143], v[166:167]
	v_pk_mul_f32 v[166:167], v[186:187], v[170:171]
	v_pk_mul_f32 v[138:139], v[138:139], v[168:169]
	v_pk_mul_f32 v[172:173], v[182:183], v[192:193]
	v_pk_mul_f32 v[136:137], v[136:137], v[174:175]
	v_pk_mul_f32 v[170:171], v[188:189], v[198:199]
	v_add_f32_e32 v140, v140, v141
	v_add_f32_e32 v141, v176, v177
	v_add_f32_e32 v142, v142, v143
	v_add_f32_e32 v143, v166, v167
	v_add_f32_e32 v166, v138, v139
	v_add_f32_e32 v159, v172, v173
	v_add_f32_e32 v136, v136, v137
	v_add_f32_e32 v137, v170, v171
	v_cvt_pk_bf16_f32 v138, v159, v140
	v_cvt_pk_bf16_f32 v139, v141, v142
	v_cvt_pk_bf16_f32 v140, v143, v136
	v_cvt_pk_bf16_f32 v141, v137, v166
	global_load_dwordx4 v[166:169], v[178:179], off offset:256 nt
	global_load_dwordx4 v[170:173], v[180:181], off offset:2304 nt
	global_load_dwordx4 v[174:177], v[180:181], off offset:256 nt
	v_lshl_add_u64 v[142:143], s[60:61], 0, v[152:153]
	v_lshl_add_u64 v[142:143], v[142:143], 0, v[156:157]
	v_pk_mul_f32 v[130:131], v[130:131], v[14:15]
	v_pk_mul_f32 v[128:129], v[128:129], v[12:13]
	v_pk_mul_f32 v[132:133], v[132:133], v[8:9]
	v_or_b32_e32 v136, 16, v158
	v_pk_mul_f32 v[134:135], v[134:135], v[10:11]
	v_mov_b32_e32 v181, v128
	v_mov_b32_e32 v183, v130
	v_mov_b32_e32 v185, v132
	global_store_dwordx4 v[142:143], v[138:141], off
	v_ashrrev_i32_e32 v137, 31, v136
	v_mov_b32_e32 v187, v134
	v_lshlrev_b64 v[152:153], 12, v[136:137]
	v_lshlrev_b64 v[136:137], 11, v[136:137]
	v_lshl_add_u64 v[178:179], s[46:47], 0, v[136:137]
	v_lshl_add_u64 v[152:153], s[62:63], 0, v[152:153]
	v_lshl_add_u64 v[178:179], v[178:179], 0, v[156:157]
	v_lshl_add_u64 v[152:153], v[152:153], 0, v[156:157]
	v_pk_mul_f32 v[126:127], v[126:127], v[30:31]
	v_pk_mul_f32 v[124:125], v[124:125], v[28:29]
	v_pk_mul_f32 v[122:123], v[122:123], v[26:27]
	v_pk_mul_f32 v[120:121], v[120:121], v[24:25]
	v_lshl_add_u64 v[136:137], s[60:61], 0, v[136:137]
	v_lshl_add_u64 v[136:137], v[136:137], 0, v[156:157]
	v_pk_mul_f32 v[114:115], v[114:115], v[14:15]
	v_pk_mul_f32 v[112:113], v[112:113], v[12:13]
	v_pk_mul_f32 v[116:117], v[116:117], v[8:9]
	v_pk_mul_f32 v[118:119], v[118:119], v[10:11]
	v_pk_mul_f32 v[110:111], v[110:111], v[30:31]
	v_pk_mul_f32 v[108:109], v[108:109], v[28:29]
	v_pk_mul_f32 v[106:107], v[106:107], v[26:27]
	v_pk_mul_f32 v[104:105], v[104:105], v[24:25]
	v_pk_mul_f32 v[98:99], v[98:99], v[14:15]
	v_pk_mul_f32 v[96:97], v[96:97], v[12:13]
	v_pk_mul_f32 v[100:101], v[100:101], v[8:9]
	v_pk_mul_f32 v[102:103], v[102:103], v[10:11]
	v_pk_mul_f32 v[94:95], v[94:95], v[30:31]
	v_pk_mul_f32 v[92:93], v[92:93], v[28:29]
	v_pk_mul_f32 v[90:91], v[90:91], v[26:27]
	v_pk_mul_f32 v[88:89], v[88:89], v[24:25]
	v_pk_mul_f32 v[82:83], v[82:83], v[14:15]
	v_pk_mul_f32 v[80:81], v[80:81], v[12:13]
	v_pk_mul_f32 v[84:85], v[84:85], v[8:9]
	v_pk_mul_f32 v[86:87], v[86:87], v[10:11]
	v_pk_mul_f32 v[78:79], v[78:79], v[30:31]
	v_pk_mul_f32 v[76:77], v[76:77], v[28:29]
	v_pk_mul_f32 v[74:75], v[74:75], v[26:27]
	v_pk_mul_f32 v[72:73], v[72:73], v[24:25]
	v_pk_mul_f32 v[66:67], v[66:67], v[14:15]
	v_pk_mul_f32 v[64:65], v[64:65], v[12:13]
	v_pk_mul_f32 v[68:69], v[68:69], v[8:9]
	v_pk_mul_f32 v[70:71], v[70:71], v[10:11]
	v_pk_mul_f32 v[62:63], v[62:63], v[30:31]
	v_pk_mul_f32 v[60:61], v[60:61], v[28:29]
	v_pk_mul_f32 v[58:59], v[58:59], v[26:27]
	v_pk_mul_f32 v[56:57], v[56:57], v[24:25]
	v_pk_mul_f32 v[50:51], v[50:51], v[14:15]
	v_pk_mul_f32 v[48:49], v[48:49], v[12:13]
	v_pk_mul_f32 v[52:53], v[52:53], v[8:9]
	v_pk_mul_f32 v[54:55], v[54:55], v[10:11]
	v_pk_mul_f32 v[46:47], v[46:47], v[30:31]
	v_pk_mul_f32 v[44:45], v[44:45], v[28:29]
	v_pk_mul_f32 v[42:43], v[42:43], v[26:27]
	v_pk_mul_f32 v[40:41], v[40:41], v[24:25]
	v_pk_mul_f32 v[34:35], v[34:35], v[14:15]
	v_pk_mul_f32 v[32:33], v[32:33], v[12:13]
	v_pk_mul_f32 v[36:37], v[36:37], v[8:9]
	v_pk_mul_f32 v[38:39], v[38:39], v[10:11]
	v_pk_mul_f32 v[22:23], v[22:23], v[30:31]
	v_pk_mul_f32 v[20:21], v[20:21], v[28:29]
	v_pk_mul_f32 v[18:19], v[18:19], v[26:27]
	v_pk_mul_f32 v[16:17], v[16:17], v[24:25]
	v_mov_b32_e32 v25, v20
	v_mov_b32_e32 v27, v22
	v_mov_b32_e32 v29, v16
	v_mov_b32_e32 v31, v18
	s_waitcnt vmcnt(3)
; __device__ __forceinline__ float bf_lo(unsigned w) { return __uint_as_float(w << 16); }
; __device__ __forceinline__ float bf_hi(unsigned w) { return __uint_as_float(w & 0xffff0000u); }
; __device__ __forceinline__ u32x4 pack8(const f32x4 a, const f32x4 b) { u32x4 w; w.x = cvt_pk_bf16(a[0], a[1]); w.y = cvt_pk_bf16(a[2], a[3]); w.z = cvt_pk_bf16(b[0], b[1]); w.w = cvt_pk_bf16(b[2], b[3]); return w; }
;     __device__ __forceinline__ void operator()(const f32x4 (&acc)[2][2][4][2], const Unit& u, int wr, int wc, int fr, int fq) const {
;     ...
;         for (int ai = 0; ai < 2; ++ai)
; #pragma unroll
;             for (int m = 0; m < 4; ++m) {
;                 const size_t row = (size_t)(row0 + ai * HALF + m * 16);
; #pragma unroll
;                 for (int bj = 0; bj < 2; ++bj) {
;                     const int c = col0 + bj * HALF;
;                     const u32x4 a8 = __builtin_nontemporal_load((const u32x4*)(A + row * 1024 + c)), ga = __builtin_nontemporal_load((const u32x4*)(G + row * 2048 + c)), gp = __builtin_nontemporal_load((const u32x4*)(G + row * 2048 + 1024 + c));
;                     const f32x4 y0 = acc[ai][bj][m][0] * ps[bj][0], y1 = acc[ai][bj][m][1] * ps[bj][1];
;                     f32x4 o0, o1;
;                     o0[0] = bf_lo(ga.x) * bf_lo(a8.x) + bf_lo(gp.x) * y0[0]; o0[1] = bf_hi(ga.x) * bf_hi(a8.x) + bf_hi(gp.x) * y0[1];
;                     o0[2] = bf_lo(ga.y) * bf_lo(a8.y) + bf_lo(gp.y) * y0[2]; o0[3] = bf_hi(ga.y) * bf_hi(a8.y) + bf_hi(gp.y) * y0[3];
;                     o1[0] = bf_lo(ga.z) * bf_lo(a8.z) + bf_lo(gp.z) * y1[0]; o1[1] = bf_hi(ga.z) * bf_hi(a8.z) + bf_hi(gp.z) * y1[1];
;                     o1[2] = bf_lo(ga.w) * bf_lo(a8.w) + bf_lo(gp.w) * y1[2]; o1[3] = bf_hi(ga.w) * bf_hi(a8.w) + bf_hi(gp.w) * y1[3];
;                     __builtin_nontemporal_store(pack8(o0, o1), (u32x4*)(Mg + row * 1024 + c));
;                 }
;                 asm volatile("" ::: "memory");
;             }
	v_lshlrev_b32_e32 v180, 16, v166
	s_waitcnt vmcnt(2)
	v_lshlrev_b32_e32 v139, 16, v170
	v_and_b32_e32 v128, 0xffff0000, v166
	v_and_b32_e32 v141, 0xffff0000, v170
	s_waitcnt vmcnt(1)
	v_and_b32_e32 v140, 0xffff0000, v174
	v_lshlrev_b32_e32 v182, 16, v167
	v_lshlrev_b32_e32 v189, 16, v171
	v_lshlrev_b32_e32 v188, 16, v175
	v_and_b32_e32 v130, 0xffff0000, v167
	v_and_b32_e32 v167, 0xffff0000, v171
	v_and_b32_e32 v166, 0xffff0000, v175
	v_lshlrev_b32_e32 v184, 16, v168
	v_lshlrev_b32_e32 v171, 16, v172
	v_lshlrev_b32_e32 v170, 16, v176
	v_lshlrev_b32_e32 v138, 16, v174
	v_and_b32_e32 v132, 0xffff0000, v168
	v_and_b32_e32 v175, 0xffff0000, v172
	v_and_b32_e32 v174, 0xffff0000, v176
	v_lshlrev_b32_e32 v186, 16, v169
	v_lshlrev_b32_e32 v193, 16, v173
	v_lshlrev_b32_e32 v192, 16, v177
	v_and_b32_e32 v134, 0xffff0000, v169
	v_and_b32_e32 v169, 0xffff0000, v173
	v_and_b32_e32 v168, 0xffff0000, v177
	v_pk_mul_f32 v[128:129], v[128:129], v[140:141]
	v_pk_mul_f32 v[140:141], v[182:183], v[188:189]
	v_pk_mul_f32 v[130:131], v[130:131], v[166:167]
	v_pk_mul_f32 v[166:167], v[184:185], v[170:171]
	v_pk_mul_f32 v[138:139], v[180:181], v[138:139]
	v_pk_mul_f32 v[132:133], v[132:133], v[174:175]
	v_pk_mul_f32 v[170:171], v[186:187], v[192:193]
	v_pk_mul_f32 v[134:135], v[134:135], v[168:169]
	v_add_f32_e32 v128, v128, v129
	v_add_f32_e32 v129, v140, v141
	v_add_f32_e32 v130, v130, v131
	v_add_f32_e32 v131, v166, v167
	v_add_f32_e32 v138, v138, v139
	v_add_f32_e32 v132, v132, v133
	v_add_f32_e32 v133, v170, v171
	v_add_f32_e32 v134, v134, v135
	v_cvt_pk_bf16_f32 v128, v138, v128
	v_cvt_pk_bf16_f32 v129, v129, v130
	v_cvt_pk_bf16_f32 v130, v131, v132
	v_cvt_pk_bf16_f32 v131, v133, v134
	global_store_dwordx4 v[142:143], v[128:131], off offset:256
	global_load_dwordx4 v[128:131], v[178:179], off nt
	global_load_dwordx4 v[132:135], v[152:153], off offset:2048 nt
	global_load_dwordx4 v[138:141], v[152:153], off nt
	v_mov_b32_e32 v143, v124
	v_mov_b32_e32 v167, v126
	v_mov_b32_e32 v169, v120
	v_mov_b32_e32 v171, v122
	v_pk_mul_f32 v[2:3], v[2:3], v[10:11]
	v_pk_mul_f32 v[0:1], v[0:1], v[8:9]
	v_pk_mul_f32 v[6:7], v[6:7], v[14:15]
	v_pk_mul_f32 v[4:5], v[4:5], v[12:13]
	v_mov_b32_e32 v13, v0
	v_mov_b32_e32 v15, v2
	v_mov_b32_e32 v9, v4
	v_mov_b32_e32 v11, v6
	s_waitcnt vmcnt(2)
	v_lshlrev_b32_e32 v142, 16, v128
	s_waitcnt vmcnt(1)
	v_lshlrev_b32_e32 v173, 16, v132
	s_waitcnt vmcnt(0)
	v_lshlrev_b32_e32 v172, 16, v138
	v_and_b32_e32 v124, 0xffff0000, v128
	v_and_b32_e32 v175, 0xffff0000, v132
	v_and_b32_e32 v174, 0xffff0000, v138
	v_lshlrev_b32_e32 v166, 16, v129
	v_lshlrev_b32_e32 v177, 16, v133
	v_lshlrev_b32_e32 v176, 16, v139
	v_and_b32_e32 v126, 0xffff0000, v129
	v_and_b32_e32 v129, 0xffff0000, v133
	v_and_b32_e32 v128, 0xffff0000, v139
	v_lshlrev_b32_e32 v168, 16, v130
	v_lshlrev_b32_e32 v133, 16, v134
	v_lshlrev_b32_e32 v132, 16, v140
	v_and_b32_e32 v120, 0xffff0000, v130
	v_lshlrev_b32_e32 v170, 16, v131
	v_and_b32_e32 v122, 0xffff0000, v131
	v_and_b32_e32 v131, 0xffff0000, v135
	v_and_b32_e32 v130, 0xffff0000, v141
	v_and_b32_e32 v139, 0xffff0000, v134
	v_and_b32_e32 v138, 0xffff0000, v140
	v_lshlrev_b32_e32 v181, 16, v135
	v_lshlrev_b32_e32 v180, 16, v141
	v_pk_mul_f32 v[134:135], v[142:143], v[172:173]
	v_pk_mul_f32 v[124:125], v[124:125], v[174:175]
	v_pk_mul_f32 v[140:141], v[166:167], v[176:177]
	v_pk_mul_f32 v[126:127], v[126:127], v[128:129]
	v_pk_mul_f32 v[128:129], v[168:169], v[132:133]
	v_pk_mul_f32 v[122:123], v[122:123], v[130:131]
	v_pk_mul_f32 v[120:121], v[120:121], v[138:139]
	v_pk_mul_f32 v[132:133], v[170:171], v[180:181]
	v_add_f32_e32 v130, v134, v135
	v_add_f32_e32 v124, v124, v125
	v_add_f32_e32 v125, v140, v141
	v_add_f32_e32 v126, v126, v127
	v_add_f32_e32 v127, v128, v129
	v_add_f32_e32 v128, v122, v123
	v_add_f32_e32 v120, v120, v121
	v_add_f32_e32 v121, v132, v133
	v_cvt_pk_bf16_f32 v122, v130, v124
	v_cvt_pk_bf16_f32 v123, v125, v126
	v_cvt_pk_bf16_f32 v124, v127, v120
	v_cvt_pk_bf16_f32 v125, v121, v128
	global_load_dwordx4 v[126:129], v[178:179], off offset:256 nt
	global_load_dwordx4 v[130:133], v[152:153], off offset:2304 nt
	global_load_dwordx4 v[138:141], v[152:153], off offset:256 nt
	v_or_b32_e32 v120, 32, v158
	v_mov_b32_e32 v153, v112
	v_mov_b32_e32 v167, v114
	v_mov_b32_e32 v169, v116
	global_store_dwordx4 v[136:137], v[122:125], off
	v_ashrrev_i32_e32 v121, 31, v120
	v_mov_b32_e32 v171, v118
	v_lshlrev_b64 v[134:135], 12, v[120:121]
	v_lshlrev_b64 v[120:121], 11, v[120:121]
	v_lshl_add_u64 v[142:143], s[46:47], 0, v[120:121]
	v_lshl_add_u64 v[134:135], s[62:63], 0, v[134:135]
	v_lshl_add_u64 v[142:143], v[142:143], 0, v[156:157]
	v_lshl_add_u64 v[134:135], v[134:135], 0, v[156:157]
	v_lshl_add_u64 v[120:121], s[60:61], 0, v[120:121]
	v_lshl_add_u64 v[120:121], v[120:121], 0, v[156:157]
	s_waitcnt vmcnt(3)
	v_lshlrev_b32_e32 v152, 16, v126
	s_waitcnt vmcnt(2)
	v_lshlrev_b32_e32 v123, 16, v130
	v_and_b32_e32 v112, 0xffff0000, v126
	v_and_b32_e32 v125, 0xffff0000, v130
	s_waitcnt vmcnt(1)
; __device__ __forceinline__ float bf_lo(unsigned w) { return __uint_as_float(w << 16); }
; __device__ __forceinline__ float bf_hi(unsigned w) { return __uint_as_float(w & 0xffff0000u); }
; __device__ __forceinline__ u32x4 pack8(const f32x4 a, const f32x4 b) { u32x4 w; w.x = cvt_pk_bf16(a[0], a[1]); w.y = cvt_pk_bf16(a[2], a[3]); w.z = cvt_pk_bf16(b[0], b[1]); w.w = cvt_pk_bf16(b[2], b[3]); return w; }
;     __device__ __forceinline__ void operator()(const f32x4 (&acc)[2][2][4][2], const Unit& u, int wr, int wc, int fr, int fq) const {
;     ...
;         for (int ai = 0; ai < 2; ++ai)
; #pragma unroll
;             for (int m = 0; m < 4; ++m) {
;                 const size_t row = (size_t)(row0 + ai * HALF + m * 16);
; #pragma unroll
;                 for (int bj = 0; bj < 2; ++bj) {
;                     const int c = col0 + bj * HALF;
;                     const u32x4 a8 = __builtin_nontemporal_load((const u32x4*)(A + row * 1024 + c)), ga = __builtin_nontemporal_load((const u32x4*)(G + row * 2048 + c)), gp = __builtin_nontemporal_load((const u32x4*)(G + row * 2048 + 1024 + c));
;                     const f32x4 y0 = acc[ai][bj][m][0] * ps[bj][0], y1 = acc[ai][bj][m][1] * ps[bj][1];
;                     f32x4 o0, o1;
;                     o0[0] = bf_lo(ga.x) * bf_lo(a8.x) + bf_lo(gp.x) * y0[0]; o0[1] = bf_hi(ga.x) * bf_hi(a8.x) + bf_hi(gp.x) * y0[1];
;                     o0[2] = bf_lo(ga.y) * bf_lo(a8.y) + bf_lo(gp.y) * y0[2]; o0[3] = bf_hi(ga.y) * bf_hi(a8.y) + bf_hi(gp.y) * y0[3];
;                     o1[0] = bf_lo(ga.z) * bf_lo(a8.z) + bf_lo(gp.z) * y1[0]; o1[1] = bf_hi(ga.z) * bf_hi(a8.z) + bf_hi(gp.z) * y1[1];
;                     o1[2] = bf_lo(ga.w) * bf_lo(a8.w) + bf_lo(gp.w) * y1[2]; o1[3] = bf_hi(ga.w) * bf_hi(a8.w) + bf_hi(gp.w) * y1[3];
;                     __builtin_nontemporal_store(pack8(o0, o1), (u32x4*)(Mg + row * 1024 + c));
;                 }
;                 asm volatile("" ::: "memory");
;             }
	v_and_b32_e32 v124, 0xffff0000, v138
	v_lshlrev_b32_e32 v166, 16, v127
	v_lshlrev_b32_e32 v173, 16, v131
	v_lshlrev_b32_e32 v172, 16, v139
	v_and_b32_e32 v114, 0xffff0000, v127
	v_and_b32_e32 v127, 0xffff0000, v131
	v_and_b32_e32 v126, 0xffff0000, v139
	v_lshlrev_b32_e32 v168, 16, v128
	v_lshlrev_b32_e32 v131, 16, v132
	v_lshlrev_b32_e32 v130, 16, v140
	v_lshlrev_b32_e32 v122, 16, v138
	v_and_b32_e32 v116, 0xffff0000, v128
	v_and_b32_e32 v139, 0xffff0000, v132
	v_and_b32_e32 v138, 0xffff0000, v140
	v_lshlrev_b32_e32 v170, 16, v129
	v_lshlrev_b32_e32 v175, 16, v133
	v_lshlrev_b32_e32 v174, 16, v141
	v_and_b32_e32 v118, 0xffff0000, v129
	v_and_b32_e32 v129, 0xffff0000, v133
	v_and_b32_e32 v128, 0xffff0000, v141
	v_pk_mul_f32 v[112:113], v[112:113], v[124:125]
	v_pk_mul_f32 v[124:125], v[166:167], v[172:173]
	v_pk_mul_f32 v[114:115], v[114:115], v[126:127]
	v_pk_mul_f32 v[126:127], v[168:169], v[130:131]
	v_pk_mul_f32 v[122:123], v[152:153], v[122:123]
	v_pk_mul_f32 v[116:117], v[116:117], v[138:139]
	v_pk_mul_f32 v[130:131], v[170:171], v[174:175]
	v_pk_mul_f32 v[118:119], v[118:119], v[128:129]
	v_add_f32_e32 v112, v112, v113
	v_add_f32_e32 v113, v124, v125
	v_add_f32_e32 v114, v114, v115
	v_add_f32_e32 v115, v126, v127
	v_add_f32_e32 v122, v122, v123
	v_add_f32_e32 v116, v116, v117
	v_add_f32_e32 v117, v130, v131
	v_add_f32_e32 v118, v118, v119
	v_cvt_pk_bf16_f32 v112, v122, v112
	v_cvt_pk_bf16_f32 v113, v113, v114
	v_cvt_pk_bf16_f32 v114, v115, v116
	v_cvt_pk_bf16_f32 v115, v117, v118
	global_store_dwordx4 v[136:137], v[112:115], off offset:256
	global_load_dwordx4 v[112:115], v[142:143], off nt
	global_load_dwordx4 v[116:119], v[134:135], off offset:2048 nt
	global_load_dwordx4 v[122:125], v[134:135], off nt
	v_mov_b32_e32 v127, v108
	v_mov_b32_e32 v129, v110
	v_mov_b32_e32 v131, v104
	v_mov_b32_e32 v133, v106
	s_waitcnt vmcnt(2)
	v_lshlrev_b32_e32 v126, 16, v112
	s_waitcnt vmcnt(1)
	v_lshlrev_b32_e32 v137, 16, v116
	s_waitcnt vmcnt(0)
	v_lshlrev_b32_e32 v136, 16, v122
	v_and_b32_e32 v108, 0xffff0000, v112
	v_and_b32_e32 v139, 0xffff0000, v116
	v_and_b32_e32 v138, 0xffff0000, v122
	v_lshlrev_b32_e32 v128, 16, v113
	v_lshlrev_b32_e32 v141, 16, v117
	v_lshlrev_b32_e32 v140, 16, v123
	v_and_b32_e32 v110, 0xffff0000, v113
	v_and_b32_e32 v113, 0xffff0000, v117
	v_and_b32_e32 v112, 0xffff0000, v123
	v_lshlrev_b32_e32 v130, 16, v114
	v_lshlrev_b32_e32 v117, 16, v118
	v_lshlrev_b32_e32 v116, 16, v124
	v_and_b32_e32 v104, 0xffff0000, v114
	v_lshlrev_b32_e32 v132, 16, v115
	v_and_b32_e32 v106, 0xffff0000, v115
	v_and_b32_e32 v115, 0xffff0000, v119
	v_and_b32_e32 v114, 0xffff0000, v125
	v_and_b32_e32 v123, 0xffff0000, v118
	v_and_b32_e32 v122, 0xffff0000, v124
	v_lshlrev_b32_e32 v153, 16, v119
	v_lshlrev_b32_e32 v152, 16, v125
	v_pk_mul_f32 v[118:119], v[126:127], v[136:137]
	v_pk_mul_f32 v[108:109], v[108:109], v[138:139]
	v_pk_mul_f32 v[124:125], v[128:129], v[140:141]
	v_pk_mul_f32 v[110:111], v[110:111], v[112:113]
	v_pk_mul_f32 v[112:113], v[130:131], v[116:117]
	v_pk_mul_f32 v[106:107], v[106:107], v[114:115]
	v_pk_mul_f32 v[104:105], v[104:105], v[122:123]
	v_pk_mul_f32 v[116:117], v[132:133], v[152:153]
	v_add_f32_e32 v114, v118, v119
	v_add_f32_e32 v108, v108, v109
	v_add_f32_e32 v109, v124, v125
	v_add_f32_e32 v110, v110, v111
	v_add_f32_e32 v111, v112, v113
	v_add_f32_e32 v112, v106, v107
	v_add_f32_e32 v104, v104, v105
	v_add_f32_e32 v105, v116, v117
	v_cvt_pk_bf16_f32 v106, v114, v108
	v_cvt_pk_bf16_f32 v107, v109, v110
	v_cvt_pk_bf16_f32 v108, v111, v104
	v_cvt_pk_bf16_f32 v109, v105, v112
	global_load_dwordx4 v[110:113], v[142:143], off offset:256 nt
	global_load_dwordx4 v[114:117], v[134:135], off offset:2304 nt
	global_load_dwordx4 v[122:125], v[134:135], off offset:256 nt
	v_or_b32_e32 v104, 48, v158
	v_mov_b32_e32 v129, v96
	v_mov_b32_e32 v131, v98
	v_mov_b32_e32 v133, v100
	global_store_dwordx4 v[120:121], v[106:109], off
	v_ashrrev_i32_e32 v105, 31, v104
	v_mov_b32_e32 v135, v102
	v_lshlrev_b64 v[118:119], 12, v[104:105]
	v_lshlrev_b64 v[104:105], 11, v[104:105]
	v_lshl_add_u64 v[126:127], s[46:47], 0, v[104:105]
	v_lshl_add_u64 v[118:119], s[62:63], 0, v[118:119]
	v_lshl_add_u64 v[126:127], v[126:127], 0, v[156:157]
	v_lshl_add_u64 v[118:119], v[118:119], 0, v[156:157]
	v_lshl_add_u64 v[104:105], s[60:61], 0, v[104:105]
	v_lshl_add_u64 v[104:105], v[104:105], 0, v[156:157]
	s_waitcnt vmcnt(3)
	v_lshlrev_b32_e32 v128, 16, v110
	s_waitcnt vmcnt(2)
	v_lshlrev_b32_e32 v107, 16, v114
	v_and_b32_e32 v96, 0xffff0000, v110
	v_and_b32_e32 v109, 0xffff0000, v114
	s_waitcnt vmcnt(1)
	v_and_b32_e32 v108, 0xffff0000, v122
	v_lshlrev_b32_e32 v130, 16, v111
	v_lshlrev_b32_e32 v137, 16, v115
	v_lshlrev_b32_e32 v136, 16, v123
	v_and_b32_e32 v98, 0xffff0000, v111
	v_and_b32_e32 v111, 0xffff0000, v115
	v_and_b32_e32 v110, 0xffff0000, v123
	v_lshlrev_b32_e32 v132, 16, v112
	v_lshlrev_b32_e32 v115, 16, v116
	v_lshlrev_b32_e32 v114, 16, v124
	v_lshlrev_b32_e32 v106, 16, v122
	v_and_b32_e32 v100, 0xffff0000, v112
	v_and_b32_e32 v123, 0xffff0000, v116
	v_and_b32_e32 v122, 0xffff0000, v124
	v_lshlrev_b32_e32 v134, 16, v113
	v_lshlrev_b32_e32 v139, 16, v117
	v_lshlrev_b32_e32 v138, 16, v125
	v_and_b32_e32 v102, 0xffff0000, v113
	v_and_b32_e32 v113, 0xffff0000, v117
	v_and_b32_e32 v112, 0xffff0000, v125
	v_pk_mul_f32 v[96:97], v[96:97], v[108:109]
	v_pk_mul_f32 v[108:109], v[130:131], v[136:137]
	v_pk_mul_f32 v[98:99], v[98:99], v[110:111]
	v_pk_mul_f32 v[110:111], v[132:133], v[114:115]
	v_pk_mul_f32 v[106:107], v[128:129], v[106:107]
	v_pk_mul_f32 v[100:101], v[100:101], v[122:123]
	v_pk_mul_f32 v[114:115], v[134:135], v[138:139]
	v_pk_mul_f32 v[102:103], v[102:103], v[112:113]
	v_add_f32_e32 v96, v96, v97
	v_add_f32_e32 v97, v108, v109
	v_add_f32_e32 v98, v98, v99
	v_add_f32_e32 v99, v110, v111
	v_add_f32_e32 v106, v106, v107
	v_add_f32_e32 v100, v100, v101
	v_add_f32_e32 v101, v114, v115
	v_add_f32_e32 v102, v102, v103
	v_cvt_pk_bf16_f32 v96, v106, v96
	v_cvt_pk_bf16_f32 v97, v97, v98
	v_cvt_pk_bf16_f32 v98, v99, v100
	v_cvt_pk_bf16_f32 v99, v101, v102
	global_store_dwordx4 v[120:121], v[96:99], off offset:256
	global_load_dwordx4 v[96:99], v[126:127], off nt
	global_load_dwordx4 v[100:103], v[118:119], off offset:2048 nt
	global_load_dwordx4 v[106:109], v[118:119], off nt
	v_mov_b32_e32 v111, v92
	v_mov_b32_e32 v113, v94
	v_mov_b32_e32 v115, v88
	v_mov_b32_e32 v117, v90
	s_waitcnt vmcnt(2)
; __device__ __forceinline__ float bf_lo(unsigned w) { return __uint_as_float(w << 16); }
; __device__ __forceinline__ float bf_hi(unsigned w) { return __uint_as_float(w & 0xffff0000u); }
; __device__ __forceinline__ u32x4 pack8(const f32x4 a, const f32x4 b) { u32x4 w; w.x = cvt_pk_bf16(a[0], a[1]); w.y = cvt_pk_bf16(a[2], a[3]); w.z = cvt_pk_bf16(b[0], b[1]); w.w = cvt_pk_bf16(b[2], b[3]); return w; }
;     __device__ __forceinline__ void operator()(const f32x4 (&acc)[2][2][4][2], const Unit& u, int wr, int wc, int fr, int fq) const {
;     ...
;         for (int ai = 0; ai < 2; ++ai)
; #pragma unroll
;             for (int m = 0; m < 4; ++m) {
;                 const size_t row = (size_t)(row0 + ai * HALF + m * 16);
; #pragma unroll
;                 for (int bj = 0; bj < 2; ++bj) {
;                     const int c = col0 + bj * HALF;
;                     const u32x4 a8 = __builtin_nontemporal_load((const u32x4*)(A + row * 1024 + c)), ga = __builtin_nontemporal_load((const u32x4*)(G + row * 2048 + c)), gp = __builtin_nontemporal_load((const u32x4*)(G + row * 2048 + 1024 + c));
;                     const f32x4 y0 = acc[ai][bj][m][0] * ps[bj][0], y1 = acc[ai][bj][m][1] * ps[bj][1];
;                     f32x4 o0, o1;
;                     o0[0] = bf_lo(ga.x) * bf_lo(a8.x) + bf_lo(gp.x) * y0[0]; o0[1] = bf_hi(ga.x) * bf_hi(a8.x) + bf_hi(gp.x) * y0[1];
;                     o0[2] = bf_lo(ga.y) * bf_lo(a8.y) + bf_lo(gp.y) * y0[2]; o0[3] = bf_hi(ga.y) * bf_hi(a8.y) + bf_hi(gp.y) * y0[3];
;                     o1[0] = bf_lo(ga.z) * bf_lo(a8.z) + bf_lo(gp.z) * y1[0]; o1[1] = bf_hi(ga.z) * bf_hi(a8.z) + bf_hi(gp.z) * y1[1];
;                     o1[2] = bf_lo(ga.w) * bf_lo(a8.w) + bf_lo(gp.w) * y1[2]; o1[3] = bf_hi(ga.w) * bf_hi(a8.w) + bf_hi(gp.w) * y1[3];
;                     __builtin_nontemporal_store(pack8(o0, o1), (u32x4*)(Mg + row * 1024 + c));
;                 }
;                 asm volatile("" ::: "memory");
;             }
	v_lshlrev_b32_e32 v110, 16, v96
	s_waitcnt vmcnt(1)
	v_lshlrev_b32_e32 v121, 16, v100
	s_waitcnt vmcnt(0)
	v_lshlrev_b32_e32 v120, 16, v106
	v_and_b32_e32 v92, 0xffff0000, v96
	v_and_b32_e32 v123, 0xffff0000, v100
	v_and_b32_e32 v122, 0xffff0000, v106
	v_lshlrev_b32_e32 v112, 16, v97
	v_lshlrev_b32_e32 v125, 16, v101
	v_lshlrev_b32_e32 v124, 16, v107
	v_and_b32_e32 v94, 0xffff0000, v97
	v_and_b32_e32 v97, 0xffff0000, v101
	v_and_b32_e32 v96, 0xffff0000, v107
	v_lshlrev_b32_e32 v114, 16, v98
	v_lshlrev_b32_e32 v101, 16, v102
	v_lshlrev_b32_e32 v100, 16, v108
	v_and_b32_e32 v88, 0xffff0000, v98
	v_lshlrev_b32_e32 v116, 16, v99
	v_and_b32_e32 v90, 0xffff0000, v99
	v_and_b32_e32 v99, 0xffff0000, v103
	v_and_b32_e32 v98, 0xffff0000, v109
	v_and_b32_e32 v107, 0xffff0000, v102
	v_and_b32_e32 v106, 0xffff0000, v108
	v_lshlrev_b32_e32 v129, 16, v103
	v_lshlrev_b32_e32 v128, 16, v109
	v_pk_mul_f32 v[102:103], v[110:111], v[120:121]
	v_pk_mul_f32 v[92:93], v[92:93], v[122:123]
	v_pk_mul_f32 v[108:109], v[112:113], v[124:125]
	v_pk_mul_f32 v[94:95], v[94:95], v[96:97]
	v_pk_mul_f32 v[96:97], v[114:115], v[100:101]
	v_pk_mul_f32 v[90:91], v[90:91], v[98:99]
	v_pk_mul_f32 v[88:89], v[88:89], v[106:107]
	v_pk_mul_f32 v[100:101], v[116:117], v[128:129]
	v_add_f32_e32 v98, v102, v103
	v_add_f32_e32 v92, v92, v93
	v_add_f32_e32 v93, v108, v109
	v_add_f32_e32 v94, v94, v95
	v_add_f32_e32 v95, v96, v97
	v_add_f32_e32 v96, v90, v91
	v_add_f32_e32 v88, v88, v89
	v_add_f32_e32 v89, v100, v101
	v_cvt_pk_bf16_f32 v90, v98, v92
	v_cvt_pk_bf16_f32 v91, v93, v94
	v_cvt_pk_bf16_f32 v92, v95, v88
	v_cvt_pk_bf16_f32 v93, v89, v96
	global_load_dwordx4 v[94:97], v[126:127], off offset:256 nt
	global_load_dwordx4 v[98:101], v[118:119], off offset:2304 nt
	global_load_dwordx4 v[106:109], v[118:119], off offset:256 nt
	v_add_u32_e32 v88, 0x80, v158
	v_mov_b32_e32 v113, v80
	v_mov_b32_e32 v115, v82
	v_mov_b32_e32 v117, v84
	global_store_dwordx4 v[104:105], v[90:93], off
	v_ashrrev_i32_e32 v89, 31, v88
	v_mov_b32_e32 v119, v86
	v_lshlrev_b64 v[102:103], 12, v[88:89]
	v_lshlrev_b64 v[88:89], 11, v[88:89]
	v_lshl_add_u64 v[110:111], s[46:47], 0, v[88:89]
	v_lshl_add_u64 v[102:103], s[62:63], 0, v[102:103]
	v_lshl_add_u64 v[110:111], v[110:111], 0, v[156:157]
	v_lshl_add_u64 v[102:103], v[102:103], 0, v[156:157]
	v_lshl_add_u64 v[88:89], s[60:61], 0, v[88:89]
	v_lshl_add_u64 v[88:89], v[88:89], 0, v[156:157]
	s_waitcnt vmcnt(3)
	v_lshlrev_b32_e32 v112, 16, v94
	s_waitcnt vmcnt(2)
	v_lshlrev_b32_e32 v91, 16, v98
	v_and_b32_e32 v80, 0xffff0000, v94
	v_and_b32_e32 v93, 0xffff0000, v98
	s_waitcnt vmcnt(1)
	v_and_b32_e32 v92, 0xffff0000, v106
	v_lshlrev_b32_e32 v114, 16, v95
	v_lshlrev_b32_e32 v121, 16, v99
	v_lshlrev_b32_e32 v120, 16, v107
	v_and_b32_e32 v82, 0xffff0000, v95
	v_and_b32_e32 v95, 0xffff0000, v99
	v_and_b32_e32 v94, 0xffff0000, v107
	v_lshlrev_b32_e32 v116, 16, v96
	v_lshlrev_b32_e32 v99, 16, v100
	v_lshlrev_b32_e32 v98, 16, v108
	v_lshlrev_b32_e32 v90, 16, v106
	v_and_b32_e32 v84, 0xffff0000, v96
	v_and_b32_e32 v107, 0xffff0000, v100
	v_and_b32_e32 v106, 0xffff0000, v108
	v_lshlrev_b32_e32 v118, 16, v97
	v_lshlrev_b32_e32 v123, 16, v101
	v_lshlrev_b32_e32 v122, 16, v109
	v_and_b32_e32 v86, 0xffff0000, v97
	v_and_b32_e32 v97, 0xffff0000, v101
	v_and_b32_e32 v96, 0xffff0000, v109
	v_pk_mul_f32 v[80:81], v[80:81], v[92:93]
	v_pk_mul_f32 v[92:93], v[114:115], v[120:121]
	v_pk_mul_f32 v[82:83], v[82:83], v[94:95]
	v_pk_mul_f32 v[94:95], v[116:117], v[98:99]
	v_pk_mul_f32 v[90:91], v[112:113], v[90:91]
	v_pk_mul_f32 v[84:85], v[84:85], v[106:107]
	v_pk_mul_f32 v[98:99], v[118:119], v[122:123]
	v_pk_mul_f32 v[86:87], v[86:87], v[96:97]
	v_add_f32_e32 v80, v80, v81
	v_add_f32_e32 v81, v92, v93
	v_add_f32_e32 v82, v82, v83
	v_add_f32_e32 v83, v94, v95
	v_add_f32_e32 v90, v90, v91
	v_add_f32_e32 v84, v84, v85
	v_add_f32_e32 v85, v98, v99
	v_add_f32_e32 v86, v86, v87
	v_cvt_pk_bf16_f32 v80, v90, v80
	v_cvt_pk_bf16_f32 v81, v81, v82
	v_cvt_pk_bf16_f32 v82, v83, v84
	v_cvt_pk_bf16_f32 v83, v85, v86
	global_store_dwordx4 v[104:105], v[80:83], off offset:256
	global_load_dwordx4 v[80:83], v[110:111], off nt
	global_load_dwordx4 v[84:87], v[102:103], off offset:2048 nt
	global_load_dwordx4 v[90:93], v[102:103], off nt
	v_mov_b32_e32 v95, v76
	v_mov_b32_e32 v97, v78
	v_mov_b32_e32 v99, v72
	v_mov_b32_e32 v101, v74
	s_waitcnt vmcnt(2)
	v_lshlrev_b32_e32 v94, 16, v80
	s_waitcnt vmcnt(1)
	v_lshlrev_b32_e32 v105, 16, v84
	s_waitcnt vmcnt(0)
	v_lshlrev_b32_e32 v104, 16, v90
	v_and_b32_e32 v76, 0xffff0000, v80
	v_and_b32_e32 v107, 0xffff0000, v84
	v_and_b32_e32 v106, 0xffff0000, v90
	v_lshlrev_b32_e32 v96, 16, v81
	v_lshlrev_b32_e32 v109, 16, v85
	v_lshlrev_b32_e32 v108, 16, v91
	v_and_b32_e32 v78, 0xffff0000, v81
	v_and_b32_e32 v81, 0xffff0000, v85
	v_and_b32_e32 v80, 0xffff0000, v91
	v_lshlrev_b32_e32 v98, 16, v82
	v_lshlrev_b32_e32 v85, 16, v86
	v_lshlrev_b32_e32 v84, 16, v92
	v_and_b32_e32 v72, 0xffff0000, v82
	v_lshlrev_b32_e32 v100, 16, v83
	v_and_b32_e32 v74, 0xffff0000, v83
	v_and_b32_e32 v83, 0xffff0000, v87
	v_and_b32_e32 v82, 0xffff0000, v93
	v_and_b32_e32 v91, 0xffff0000, v86
	v_and_b32_e32 v90, 0xffff0000, v92
	v_lshlrev_b32_e32 v113, 16, v87
	v_lshlrev_b32_e32 v112, 16, v93
	v_pk_mul_f32 v[86:87], v[94:95], v[104:105]
	v_pk_mul_f32 v[76:77], v[76:77], v[106:107]
	v_pk_mul_f32 v[92:93], v[96:97], v[108:109]
	v_pk_mul_f32 v[78:79], v[78:79], v[80:81]
	v_pk_mul_f32 v[80:81], v[98:99], v[84:85]
	v_pk_mul_f32 v[74:75], v[74:75], v[82:83]
	v_pk_mul_f32 v[72:73], v[72:73], v[90:91]
	v_pk_mul_f32 v[84:85], v[100:101], v[112:113]
	v_add_f32_e32 v82, v86, v87
	v_add_f32_e32 v76, v76, v77
	v_add_f32_e32 v77, v92, v93
	v_add_f32_e32 v78, v78, v79
	v_add_f32_e32 v79, v80, v81
	v_add_f32_e32 v80, v74, v75
	v_add_f32_e32 v72, v72, v73
	v_add_f32_e32 v73, v84, v85
	v_cvt_pk_bf16_f32 v74, v82, v76
	v_cvt_pk_bf16_f32 v75, v77, v78
	v_cvt_pk_bf16_f32 v76, v79, v72
	v_cvt_pk_bf16_f32 v77, v73, v80
	global_load_dwordx4 v[78:81], v[110:111], off offset:256 nt
	global_load_dwordx4 v[82:85], v[102:103], off offset:2304 nt
	global_load_dwordx4 v[90:93], v[102:103], off offset:256 nt
	v_add_u32_e32 v72, 0x90, v158
	v_mov_b32_e32 v97, v64
	v_mov_b32_e32 v99, v66
	v_mov_b32_e32 v101, v68
	global_store_dwordx4 v[88:89], v[74:77], off
	v_ashrrev_i32_e32 v73, 31, v72
	v_mov_b32_e32 v103, v70
	v_lshlrev_b64 v[86:87], 12, v[72:73]
	v_lshlrev_b64 v[72:73], 11, v[72:73]
	v_lshl_add_u64 v[94:95], s[46:47], 0, v[72:73]
	v_lshl_add_u64 v[86:87], s[62:63], 0, v[86:87]
	v_lshl_add_u64 v[94:95], v[94:95], 0, v[156:157]
	v_lshl_add_u64 v[86:87], v[86:87], 0, v[156:157]
	v_lshl_add_u64 v[72:73], s[60:61], 0, v[72:73]
	v_lshl_add_u64 v[72:73], v[72:73], 0, v[156:157]
	s_waitcnt vmcnt(3)
; __device__ __forceinline__ float bf_lo(unsigned w) { return __uint_as_float(w << 16); }
; __device__ __forceinline__ float bf_hi(unsigned w) { return __uint_as_float(w & 0xffff0000u); }
; __device__ __forceinline__ u32x4 pack8(const f32x4 a, const f32x4 b) { u32x4 w; w.x = cvt_pk_bf16(a[0], a[1]); w.y = cvt_pk_bf16(a[2], a[3]); w.z = cvt_pk_bf16(b[0], b[1]); w.w = cvt_pk_bf16(b[2], b[3]); return w; }
;     __device__ __forceinline__ void operator()(const f32x4 (&acc)[2][2][4][2], const Unit& u, int wr, int wc, int fr, int fq) const {
;     ...
;         for (int ai = 0; ai < 2; ++ai)
; #pragma unroll
;             for (int m = 0; m < 4; ++m) {
;                 const size_t row = (size_t)(row0 + ai * HALF + m * 16);
; #pragma unroll
;                 for (int bj = 0; bj < 2; ++bj) {
;                     const int c = col0 + bj * HALF;
;                     const u32x4 a8 = __builtin_nontemporal_load((const u32x4*)(A + row * 1024 + c)), ga = __builtin_nontemporal_load((const u32x4*)(G + row * 2048 + c)), gp = __builtin_nontemporal_load((const u32x4*)(G + row * 2048 + 1024 + c));
;                     const f32x4 y0 = acc[ai][bj][m][0] * ps[bj][0], y1 = acc[ai][bj][m][1] * ps[bj][1];
;                     f32x4 o0, o1;
;                     o0[0] = bf_lo(ga.x) * bf_lo(a8.x) + bf_lo(gp.x) * y0[0]; o0[1] = bf_hi(ga.x) * bf_hi(a8.x) + bf_hi(gp.x) * y0[1];
;                     o0[2] = bf_lo(ga.y) * bf_lo(a8.y) + bf_lo(gp.y) * y0[2]; o0[3] = bf_hi(ga.y) * bf_hi(a8.y) + bf_hi(gp.y) * y0[3];
;                     o1[0] = bf_lo(ga.z) * bf_lo(a8.z) + bf_lo(gp.z) * y1[0]; o1[1] = bf_hi(ga.z) * bf_hi(a8.z) + bf_hi(gp.z) * y1[1];
;                     o1[2] = bf_lo(ga.w) * bf_lo(a8.w) + bf_lo(gp.w) * y1[2]; o1[3] = bf_hi(ga.w) * bf_hi(a8.w) + bf_hi(gp.w) * y1[3];
;                     __builtin_nontemporal_store(pack8(o0, o1), (u32x4*)(Mg + row * 1024 + c));
;                 }
;                 asm volatile("" ::: "memory");
;             }
	v_lshlrev_b32_e32 v96, 16, v78
	s_waitcnt vmcnt(2)
	v_lshlrev_b32_e32 v75, 16, v82
	v_and_b32_e32 v64, 0xffff0000, v78
	v_and_b32_e32 v77, 0xffff0000, v82
	s_waitcnt vmcnt(1)
	v_and_b32_e32 v76, 0xffff0000, v90
	v_lshlrev_b32_e32 v98, 16, v79
	v_lshlrev_b32_e32 v105, 16, v83
	v_lshlrev_b32_e32 v104, 16, v91
	v_and_b32_e32 v66, 0xffff0000, v79
	v_and_b32_e32 v79, 0xffff0000, v83
	v_and_b32_e32 v78, 0xffff0000, v91
	v_lshlrev_b32_e32 v100, 16, v80
	v_lshlrev_b32_e32 v83, 16, v84
	v_lshlrev_b32_e32 v82, 16, v92
	v_lshlrev_b32_e32 v74, 16, v90
	v_and_b32_e32 v68, 0xffff0000, v80
	v_and_b32_e32 v91, 0xffff0000, v84
	v_and_b32_e32 v90, 0xffff0000, v92
	v_lshlrev_b32_e32 v102, 16, v81
	v_lshlrev_b32_e32 v107, 16, v85
	v_lshlrev_b32_e32 v106, 16, v93
	v_and_b32_e32 v70, 0xffff0000, v81
	v_and_b32_e32 v81, 0xffff0000, v85
	v_and_b32_e32 v80, 0xffff0000, v93
	v_pk_mul_f32 v[64:65], v[64:65], v[76:77]
	v_pk_mul_f32 v[76:77], v[98:99], v[104:105]
	v_pk_mul_f32 v[66:67], v[66:67], v[78:79]
	v_pk_mul_f32 v[78:79], v[100:101], v[82:83]
	v_pk_mul_f32 v[74:75], v[96:97], v[74:75]
	v_pk_mul_f32 v[68:69], v[68:69], v[90:91]
	v_pk_mul_f32 v[82:83], v[102:103], v[106:107]
	v_pk_mul_f32 v[70:71], v[70:71], v[80:81]
	v_add_f32_e32 v64, v64, v65
	v_add_f32_e32 v65, v76, v77
	v_add_f32_e32 v66, v66, v67
	v_add_f32_e32 v67, v78, v79
	v_add_f32_e32 v74, v74, v75
	v_add_f32_e32 v68, v68, v69
	v_add_f32_e32 v69, v82, v83
	v_add_f32_e32 v70, v70, v71
	v_cvt_pk_bf16_f32 v64, v74, v64
	v_cvt_pk_bf16_f32 v65, v65, v66
	v_cvt_pk_bf16_f32 v66, v67, v68
	v_cvt_pk_bf16_f32 v67, v69, v70
	global_store_dwordx4 v[88:89], v[64:67], off offset:256
	global_load_dwordx4 v[64:67], v[94:95], off nt
	global_load_dwordx4 v[68:71], v[86:87], off offset:2048 nt
	global_load_dwordx4 v[74:77], v[86:87], off nt
	v_mov_b32_e32 v79, v60
	v_mov_b32_e32 v81, v62
	v_mov_b32_e32 v83, v56
	v_mov_b32_e32 v85, v58
	s_waitcnt vmcnt(2)
	v_lshlrev_b32_e32 v78, 16, v64
	s_waitcnt vmcnt(1)
	v_lshlrev_b32_e32 v89, 16, v68
	s_waitcnt vmcnt(0)
	v_lshlrev_b32_e32 v88, 16, v74
	v_and_b32_e32 v60, 0xffff0000, v64
	v_and_b32_e32 v91, 0xffff0000, v68
	v_and_b32_e32 v90, 0xffff0000, v74
	v_lshlrev_b32_e32 v80, 16, v65
	v_lshlrev_b32_e32 v93, 16, v69
	v_lshlrev_b32_e32 v92, 16, v75
	v_and_b32_e32 v62, 0xffff0000, v65
	v_and_b32_e32 v65, 0xffff0000, v69
	v_and_b32_e32 v64, 0xffff0000, v75
	v_lshlrev_b32_e32 v82, 16, v66
	v_lshlrev_b32_e32 v69, 16, v70
	v_lshlrev_b32_e32 v68, 16, v76
	v_and_b32_e32 v56, 0xffff0000, v66
	v_lshlrev_b32_e32 v84, 16, v67
	v_and_b32_e32 v58, 0xffff0000, v67
	v_and_b32_e32 v67, 0xffff0000, v71
	v_and_b32_e32 v66, 0xffff0000, v77
	v_and_b32_e32 v75, 0xffff0000, v70
	v_and_b32_e32 v74, 0xffff0000, v76
	v_lshlrev_b32_e32 v97, 16, v71
	v_lshlrev_b32_e32 v96, 16, v77
	v_pk_mul_f32 v[70:71], v[78:79], v[88:89]
	v_pk_mul_f32 v[60:61], v[60:61], v[90:91]
	v_pk_mul_f32 v[76:77], v[80:81], v[92:93]
	v_pk_mul_f32 v[62:63], v[62:63], v[64:65]
	v_pk_mul_f32 v[64:65], v[82:83], v[68:69]
	v_pk_mul_f32 v[58:59], v[58:59], v[66:67]
	v_pk_mul_f32 v[56:57], v[56:57], v[74:75]
	v_pk_mul_f32 v[68:69], v[84:85], v[96:97]
	v_add_f32_e32 v66, v70, v71
	v_add_f32_e32 v60, v60, v61
	v_add_f32_e32 v61, v76, v77
	v_add_f32_e32 v62, v62, v63
	v_add_f32_e32 v63, v64, v65
	v_add_f32_e32 v64, v58, v59
	v_add_f32_e32 v56, v56, v57
	v_add_f32_e32 v57, v68, v69
	v_cvt_pk_bf16_f32 v58, v66, v60
	v_cvt_pk_bf16_f32 v59, v61, v62
	v_cvt_pk_bf16_f32 v60, v63, v56
	v_cvt_pk_bf16_f32 v61, v57, v64
	global_load_dwordx4 v[62:65], v[94:95], off offset:256 nt
	global_load_dwordx4 v[66:69], v[86:87], off offset:2304 nt
	global_load_dwordx4 v[74:77], v[86:87], off offset:256 nt
	v_add_u32_e32 v56, 0xa0, v158
	v_mov_b32_e32 v81, v48
	v_mov_b32_e32 v83, v50
	v_mov_b32_e32 v85, v52
	global_store_dwordx4 v[72:73], v[58:61], off
	v_ashrrev_i32_e32 v57, 31, v56
	v_mov_b32_e32 v87, v54
	v_lshlrev_b64 v[70:71], 12, v[56:57]
	v_lshlrev_b64 v[56:57], 11, v[56:57]
	v_lshl_add_u64 v[78:79], s[46:47], 0, v[56:57]
	v_lshl_add_u64 v[70:71], s[62:63], 0, v[70:71]
	v_lshl_add_u64 v[78:79], v[78:79], 0, v[156:157]
	v_lshl_add_u64 v[70:71], v[70:71], 0, v[156:157]
	v_lshl_add_u64 v[56:57], s[60:61], 0, v[56:57]
	v_lshl_add_u64 v[56:57], v[56:57], 0, v[156:157]
	s_waitcnt vmcnt(3)
	v_lshlrev_b32_e32 v80, 16, v62
	s_waitcnt vmcnt(2)
	v_lshlrev_b32_e32 v59, 16, v66
	v_and_b32_e32 v48, 0xffff0000, v62
	v_and_b32_e32 v61, 0xffff0000, v66
	s_waitcnt vmcnt(1)
	v_and_b32_e32 v60, 0xffff0000, v74
	v_lshlrev_b32_e32 v82, 16, v63
	v_lshlrev_b32_e32 v89, 16, v67
	v_lshlrev_b32_e32 v88, 16, v75
	v_and_b32_e32 v50, 0xffff0000, v63
	v_and_b32_e32 v63, 0xffff0000, v67
	v_and_b32_e32 v62, 0xffff0000, v75
	v_lshlrev_b32_e32 v84, 16, v64
	v_lshlrev_b32_e32 v67, 16, v68
	v_lshlrev_b32_e32 v66, 16, v76
	v_lshlrev_b32_e32 v58, 16, v74
	v_and_b32_e32 v52, 0xffff0000, v64
	v_and_b32_e32 v75, 0xffff0000, v68
	v_and_b32_e32 v74, 0xffff0000, v76
	v_lshlrev_b32_e32 v86, 16, v65
	v_lshlrev_b32_e32 v91, 16, v69
	v_lshlrev_b32_e32 v90, 16, v77
	v_and_b32_e32 v54, 0xffff0000, v65
	v_and_b32_e32 v65, 0xffff0000, v69
	v_and_b32_e32 v64, 0xffff0000, v77
	v_pk_mul_f32 v[48:49], v[48:49], v[60:61]
	v_pk_mul_f32 v[60:61], v[82:83], v[88:89]
	v_pk_mul_f32 v[50:51], v[50:51], v[62:63]
	v_pk_mul_f32 v[62:63], v[84:85], v[66:67]
	v_pk_mul_f32 v[58:59], v[80:81], v[58:59]
	v_pk_mul_f32 v[52:53], v[52:53], v[74:75]
	v_pk_mul_f32 v[66:67], v[86:87], v[90:91]
	v_pk_mul_f32 v[54:55], v[54:55], v[64:65]
	v_add_f32_e32 v48, v48, v49
	v_add_f32_e32 v49, v60, v61
	v_add_f32_e32 v50, v50, v51
	v_add_f32_e32 v51, v62, v63
	v_add_f32_e32 v58, v58, v59
	v_add_f32_e32 v52, v52, v53
	v_add_f32_e32 v53, v66, v67
	v_add_f32_e32 v54, v54, v55
	v_cvt_pk_bf16_f32 v48, v58, v48
	v_cvt_pk_bf16_f32 v49, v49, v50
	v_cvt_pk_bf16_f32 v50, v51, v52
	v_cvt_pk_bf16_f32 v51, v53, v54
	global_store_dwordx4 v[72:73], v[48:51], off offset:256
	global_load_dwordx4 v[48:51], v[78:79], off nt
	global_load_dwordx4 v[52:55], v[70:71], off offset:2048 nt
	global_load_dwordx4 v[58:61], v[70:71], off nt
	v_mov_b32_e32 v63, v44
	v_mov_b32_e32 v65, v46
	v_mov_b32_e32 v67, v40
	v_mov_b32_e32 v69, v42
	s_waitcnt vmcnt(2)
; __device__ __forceinline__ float bf_lo(unsigned w) { return __uint_as_float(w << 16); }
; __device__ __forceinline__ float bf_hi(unsigned w) { return __uint_as_float(w & 0xffff0000u); }
; __device__ __forceinline__ u32x4 pack8(const f32x4 a, const f32x4 b) { u32x4 w; w.x = cvt_pk_bf16(a[0], a[1]); w.y = cvt_pk_bf16(a[2], a[3]); w.z = cvt_pk_bf16(b[0], b[1]); w.w = cvt_pk_bf16(b[2], b[3]); return w; }
;     __device__ __forceinline__ void operator()(const f32x4 (&acc)[2][2][4][2], const Unit& u, int wr, int wc, int fr, int fq) const {
;     ...
;         for (int ai = 0; ai < 2; ++ai)
; #pragma unroll
;             for (int m = 0; m < 4; ++m) {
;                 const size_t row = (size_t)(row0 + ai * HALF + m * 16);
; #pragma unroll
;                 for (int bj = 0; bj < 2; ++bj) {
;                     const int c = col0 + bj * HALF;
;                     const u32x4 a8 = __builtin_nontemporal_load((const u32x4*)(A + row * 1024 + c)), ga = __builtin_nontemporal_load((const u32x4*)(G + row * 2048 + c)), gp = __builtin_nontemporal_load((const u32x4*)(G + row * 2048 + 1024 + c));
;                     const f32x4 y0 = acc[ai][bj][m][0] * ps[bj][0], y1 = acc[ai][bj][m][1] * ps[bj][1];
;                     f32x4 o0, o1;
;                     o0[0] = bf_lo(ga.x) * bf_lo(a8.x) + bf_lo(gp.x) * y0[0]; o0[1] = bf_hi(ga.x) * bf_hi(a8.x) + bf_hi(gp.x) * y0[1];
;                     o0[2] = bf_lo(ga.y) * bf_lo(a8.y) + bf_lo(gp.y) * y0[2]; o0[3] = bf_hi(ga.y) * bf_hi(a8.y) + bf_hi(gp.y) * y0[3];
;                     o1[0] = bf_lo(ga.z) * bf_lo(a8.z) + bf_lo(gp.z) * y1[0]; o1[1] = bf_hi(ga.z) * bf_hi(a8.z) + bf_hi(gp.z) * y1[1];
;                     o1[2] = bf_lo(ga.w) * bf_lo(a8.w) + bf_lo(gp.w) * y1[2]; o1[3] = bf_hi(ga.w) * bf_hi(a8.w) + bf_hi(gp.w) * y1[3];
;                     __builtin_nontemporal_store(pack8(o0, o1), (u32x4*)(Mg + row * 1024 + c));
;                 }
;                 asm volatile("" ::: "memory");
;             }
	v_lshlrev_b32_e32 v62, 16, v48
	s_waitcnt vmcnt(1)
	v_lshlrev_b32_e32 v73, 16, v52
	s_waitcnt vmcnt(0)
	v_lshlrev_b32_e32 v72, 16, v58
	v_and_b32_e32 v44, 0xffff0000, v48
	v_and_b32_e32 v75, 0xffff0000, v52
	v_and_b32_e32 v74, 0xffff0000, v58
	v_lshlrev_b32_e32 v64, 16, v49
	v_lshlrev_b32_e32 v77, 16, v53
	v_lshlrev_b32_e32 v76, 16, v59
	v_and_b32_e32 v46, 0xffff0000, v49
	v_and_b32_e32 v49, 0xffff0000, v53
	v_and_b32_e32 v48, 0xffff0000, v59
	v_lshlrev_b32_e32 v66, 16, v50
	v_lshlrev_b32_e32 v53, 16, v54
	v_lshlrev_b32_e32 v52, 16, v60
	v_and_b32_e32 v40, 0xffff0000, v50
	v_and_b32_e32 v59, 0xffff0000, v54
	v_and_b32_e32 v58, 0xffff0000, v60
	v_lshlrev_b32_e32 v68, 16, v51
	v_lshlrev_b32_e32 v81, 16, v55
	v_lshlrev_b32_e32 v80, 16, v61
	v_and_b32_e32 v42, 0xffff0000, v51
	v_and_b32_e32 v51, 0xffff0000, v55
	v_and_b32_e32 v50, 0xffff0000, v61
	v_pk_mul_f32 v[54:55], v[62:63], v[72:73]
	v_pk_mul_f32 v[44:45], v[44:45], v[74:75]
	v_pk_mul_f32 v[60:61], v[64:65], v[76:77]
	v_pk_mul_f32 v[46:47], v[46:47], v[48:49]
	v_pk_mul_f32 v[48:49], v[66:67], v[52:53]
	v_pk_mul_f32 v[40:41], v[40:41], v[58:59]
	v_pk_mul_f32 v[52:53], v[68:69], v[80:81]
	v_pk_mul_f32 v[42:43], v[42:43], v[50:51]
	v_add_f32_e32 v50, v54, v55
	v_add_f32_e32 v44, v44, v45
	v_add_f32_e32 v45, v60, v61
	v_add_f32_e32 v46, v46, v47
	v_add_f32_e32 v47, v48, v49
	v_add_f32_e32 v48, v40, v41
	v_add_f32_e32 v49, v52, v53
	v_add_f32_e32 v43, v42, v43
	v_cvt_pk_bf16_f32 v40, v50, v44
	v_cvt_pk_bf16_f32 v41, v45, v46
	v_cvt_pk_bf16_f32 v42, v47, v48
	v_cvt_pk_bf16_f32 v43, v49, v43
	global_load_dwordx4 v[44:47], v[78:79], off offset:256 nt
	global_load_dwordx4 v[48:51], v[70:71], off offset:2304 nt
	global_load_dwordx4 v[52:55], v[70:71], off offset:256 nt
	v_add_u32_e32 v58, 0xb0, v158
	v_mov_b32_e32 v65, v32
	v_mov_b32_e32 v67, v34
	v_mov_b32_e32 v69, v36
	global_store_dwordx4 v[56:57], v[40:43], off
	v_ashrrev_i32_e32 v59, 31, v58
	v_mov_b32_e32 v71, v38
	v_lshlrev_b64 v[60:61], 12, v[58:59]
	v_lshlrev_b64 v[58:59], 11, v[58:59]
	v_lshl_add_u64 v[62:63], s[46:47], 0, v[58:59]
	v_lshl_add_u64 v[60:61], s[62:63], 0, v[60:61]
	v_lshl_add_u64 v[62:63], v[62:63], 0, v[156:157]
	v_lshl_add_u64 v[60:61], v[60:61], 0, v[156:157]
	s_waitcnt vmcnt(3)
	v_lshlrev_b32_e32 v64, 16, v44
	s_waitcnt vmcnt(2)
	v_lshlrev_b32_e32 v41, 16, v48
	v_and_b32_e32 v32, 0xffff0000, v44
	v_and_b32_e32 v43, 0xffff0000, v48
	s_waitcnt vmcnt(1)
	v_and_b32_e32 v42, 0xffff0000, v52
	v_lshlrev_b32_e32 v66, 16, v45
	v_lshlrev_b32_e32 v73, 16, v49
	v_lshlrev_b32_e32 v72, 16, v53
	v_and_b32_e32 v34, 0xffff0000, v45
	v_and_b32_e32 v45, 0xffff0000, v49
	v_and_b32_e32 v44, 0xffff0000, v53
	v_lshlrev_b32_e32 v68, 16, v46
	v_lshlrev_b32_e32 v49, 16, v50
	v_lshlrev_b32_e32 v48, 16, v54
	v_lshlrev_b32_e32 v40, 16, v52
	v_and_b32_e32 v36, 0xffff0000, v46
	v_and_b32_e32 v53, 0xffff0000, v50
	v_and_b32_e32 v52, 0xffff0000, v54
	v_lshlrev_b32_e32 v70, 16, v47
	v_lshlrev_b32_e32 v75, 16, v51
	v_lshlrev_b32_e32 v74, 16, v55
	v_and_b32_e32 v38, 0xffff0000, v47
	v_and_b32_e32 v47, 0xffff0000, v51
	v_and_b32_e32 v46, 0xffff0000, v55
	v_pk_mul_f32 v[32:33], v[32:33], v[42:43]
	v_pk_mul_f32 v[42:43], v[66:67], v[72:73]
	v_pk_mul_f32 v[34:35], v[34:35], v[44:45]
	v_pk_mul_f32 v[44:45], v[68:69], v[48:49]
	v_pk_mul_f32 v[40:41], v[64:65], v[40:41]
	v_pk_mul_f32 v[36:37], v[36:37], v[52:53]
	v_pk_mul_f32 v[48:49], v[70:71], v[74:75]
	v_pk_mul_f32 v[38:39], v[38:39], v[46:47]
	v_add_f32_e32 v32, v32, v33
	v_add_f32_e32 v33, v42, v43
	v_add_f32_e32 v34, v34, v35
	v_add_f32_e32 v35, v44, v45
	v_add_f32_e32 v40, v40, v41
	v_add_f32_e32 v36, v36, v37
	v_add_f32_e32 v37, v48, v49
	v_add_f32_e32 v38, v38, v39
	v_cvt_pk_bf16_f32 v32, v40, v32
	v_cvt_pk_bf16_f32 v33, v33, v34
	v_cvt_pk_bf16_f32 v34, v35, v36
	v_cvt_pk_bf16_f32 v35, v37, v38
	global_store_dwordx4 v[56:57], v[32:35], off offset:256
	global_load_dwordx4 v[32:35], v[62:63], off nt
	global_load_dwordx4 v[36:39], v[60:61], off offset:2048 nt
	global_load_dwordx4 v[40:43], v[60:61], off nt
	s_waitcnt vmcnt(2)
; __device__ __forceinline__ float bf_lo(unsigned w) { return __uint_as_float(w << 16); }
; __device__ __forceinline__ float bf_hi(unsigned w) { return __uint_as_float(w & 0xffff0000u); }
; __device__ __forceinline__ u32x4 pack8(const f32x4 a, const f32x4 b) { u32x4 w; w.x = cvt_pk_bf16(a[0], a[1]); w.y = cvt_pk_bf16(a[2], a[3]); w.z = cvt_pk_bf16(b[0], b[1]); w.w = cvt_pk_bf16(b[2], b[3]); return w; }
;     __device__ __forceinline__ void operator()(const f32x4 (&acc)[2][2][4][2], const Unit& u, int wr, int wc, int fr, int fq) const {
;     ...
;         for (int ai = 0; ai < 2; ++ai)
; #pragma unroll
;             for (int m = 0; m < 4; ++m) {
;                 const size_t row = (size_t)(row0 + ai * HALF + m * 16);
; #pragma unroll
;                 for (int bj = 0; bj < 2; ++bj) {
;                     const int c = col0 + bj * HALF;
;                     const u32x4 a8 = __builtin_nontemporal_load((const u32x4*)(A + row * 1024 + c)), ga = __builtin_nontemporal_load((const u32x4*)(G + row * 2048 + c)), gp = __builtin_nontemporal_load((const u32x4*)(G + row * 2048 + 1024 + c));
;                     const f32x4 y0 = acc[ai][bj][m][0] * ps[bj][0], y1 = acc[ai][bj][m][1] * ps[bj][1];
;                     f32x4 o0, o1;
;                     o0[0] = bf_lo(ga.x) * bf_lo(a8.x) + bf_lo(gp.x) * y0[0]; o0[1] = bf_hi(ga.x) * bf_hi(a8.x) + bf_hi(gp.x) * y0[1];
;                     o0[2] = bf_lo(ga.y) * bf_lo(a8.y) + bf_lo(gp.y) * y0[2]; o0[3] = bf_hi(ga.y) * bf_hi(a8.y) + bf_hi(gp.y) * y0[3];
;                     o1[0] = bf_lo(ga.z) * bf_lo(a8.z) + bf_lo(gp.z) * y1[0]; o1[1] = bf_hi(ga.z) * bf_hi(a8.z) + bf_hi(gp.z) * y1[1];
;                     o1[2] = bf_lo(ga.w) * bf_lo(a8.w) + bf_lo(gp.w) * y1[2]; o1[3] = bf_hi(ga.w) * bf_hi(a8.w) + bf_hi(gp.w) * y1[3];
;                     __builtin_nontemporal_store(pack8(o0, o1), (u32x4*)(Mg + row * 1024 + c));
;                 }
;                 asm volatile("" ::: "memory");
;             }
	v_lshlrev_b32_e32 v24, 16, v32
	s_waitcnt vmcnt(1)
	v_lshlrev_b32_e32 v45, 16, v36
	s_waitcnt vmcnt(0)
	v_lshlrev_b32_e32 v44, 16, v40
	v_and_b32_e32 v20, 0xffff0000, v32
	v_and_b32_e32 v47, 0xffff0000, v36
	v_and_b32_e32 v46, 0xffff0000, v40
	v_lshlrev_b32_e32 v26, 16, v33
	v_lshlrev_b32_e32 v49, 16, v37
	v_lshlrev_b32_e32 v48, 16, v41
	v_and_b32_e32 v22, 0xffff0000, v33
	v_and_b32_e32 v33, 0xffff0000, v37
	v_and_b32_e32 v32, 0xffff0000, v41
	v_lshlrev_b32_e32 v28, 16, v34
	v_lshlrev_b32_e32 v37, 16, v38
	v_lshlrev_b32_e32 v36, 16, v42
	v_and_b32_e32 v16, 0xffff0000, v34
	v_and_b32_e32 v41, 0xffff0000, v38
	v_and_b32_e32 v40, 0xffff0000, v42
	v_lshlrev_b32_e32 v30, 16, v35
	v_lshlrev_b32_e32 v51, 16, v39
	v_lshlrev_b32_e32 v50, 16, v43
	v_and_b32_e32 v18, 0xffff0000, v35
	v_and_b32_e32 v35, 0xffff0000, v39
	v_and_b32_e32 v34, 0xffff0000, v43
	v_pk_mul_f32 v[24:25], v[24:25], v[44:45]
	v_pk_mul_f32 v[20:21], v[20:21], v[46:47]
	v_pk_mul_f32 v[26:27], v[26:27], v[48:49]
	v_pk_mul_f32 v[22:23], v[22:23], v[32:33]
	v_pk_mul_f32 v[28:29], v[28:29], v[36:37]
	v_pk_mul_f32 v[16:17], v[16:17], v[40:41]
	v_pk_mul_f32 v[30:31], v[30:31], v[50:51]
	v_pk_mul_f32 v[18:19], v[18:19], v[34:35]
	v_add_f32_e32 v24, v24, v25
	v_add_f32_e32 v20, v20, v21
	v_add_f32_e32 v21, v26, v27
	v_add_f32_e32 v22, v22, v23
	v_add_f32_e32 v23, v28, v29
	v_add_f32_e32 v25, v16, v17
	v_add_f32_e32 v26, v30, v31
	v_add_f32_e32 v19, v18, v19
	v_cvt_pk_bf16_f32 v16, v24, v20
	v_cvt_pk_bf16_f32 v17, v21, v22
	v_cvt_pk_bf16_f32 v18, v23, v25
	v_cvt_pk_bf16_f32 v19, v26, v19
	global_load_dwordx4 v[20:23], v[62:63], off offset:256 nt
	global_load_dwordx4 v[24:27], v[60:61], off offset:2304 nt
	global_load_dwordx4 v[28:31], v[60:61], off offset:256 nt
	v_lshl_add_u64 v[32:33], s[60:61], 0, v[58:59]
	v_lshl_add_u64 v[32:33], v[32:33], 0, v[156:157]
	global_store_dwordx4 v[32:33], v[16:19], off
	s_waitcnt vmcnt(3)
	v_lshlrev_b32_e32 v12, 16, v22
	v_and_b32_e32 v0, 0xffff0000, v22
	v_lshlrev_b32_e32 v14, 16, v23
	v_and_b32_e32 v2, 0xffff0000, v23
	s_waitcnt vmcnt(2)
	v_and_b32_e32 v23, 0xffff0000, v27
	s_waitcnt vmcnt(1)
	v_and_b32_e32 v22, 0xffff0000, v31
	v_lshlrev_b32_e32 v8, 16, v20
	v_lshlrev_b32_e32 v17, 16, v24
	v_lshlrev_b32_e32 v16, 16, v28
	v_and_b32_e32 v4, 0xffff0000, v20
	v_and_b32_e32 v19, 0xffff0000, v24
	v_and_b32_e32 v18, 0xffff0000, v28
	v_lshlrev_b32_e32 v10, 16, v21
	v_lshlrev_b32_e32 v35, 16, v25
	v_lshlrev_b32_e32 v34, 16, v29
	v_and_b32_e32 v6, 0xffff0000, v21
	v_and_b32_e32 v21, 0xffff0000, v25
	v_and_b32_e32 v20, 0xffff0000, v29
	v_lshlrev_b32_e32 v25, 16, v26
	v_lshlrev_b32_e32 v24, 16, v30
	v_and_b32_e32 v29, 0xffff0000, v26
	v_and_b32_e32 v28, 0xffff0000, v30
	v_lshlrev_b32_e32 v37, 16, v27
	v_lshlrev_b32_e32 v36, 16, v31
	v_pk_mul_f32 v[2:3], v[2:3], v[22:23]
	v_pk_mul_f32 v[8:9], v[8:9], v[16:17]
	v_pk_mul_f32 v[4:5], v[4:5], v[18:19]
	v_pk_mul_f32 v[10:11], v[10:11], v[34:35]
	v_pk_mul_f32 v[6:7], v[6:7], v[20:21]
	v_pk_mul_f32 v[12:13], v[12:13], v[24:25]
	v_pk_mul_f32 v[0:1], v[0:1], v[28:29]
	v_pk_mul_f32 v[14:15], v[14:15], v[36:37]
	v_add_f32_e32 v3, v2, v3
	v_add_f32_e32 v8, v8, v9
	v_add_f32_e32 v4, v4, v5
	v_add_f32_e32 v5, v10, v11
	v_add_f32_e32 v6, v6, v7
	v_add_f32_e32 v7, v12, v13
	v_add_f32_e32 v9, v0, v1
	v_add_f32_e32 v10, v14, v15
	v_cvt_pk_bf16_f32 v0, v8, v4
	v_cvt_pk_bf16_f32 v1, v5, v6
	v_cvt_pk_bf16_f32 v2, v7, v9
	v_cvt_pk_bf16_f32 v3, v10, v3
	global_store_dwordx4 v[32:33], v[0:3], off offset:256
	s_cbranch_vccnz .LBB0_372
	s_andn2_b64 vcc, exec, s[4:5]
	s_cbranch_vccnz .LBB0_371
	s_barrier
	s_branch .LBB0_371

; template <int K> __device__ __forceinline__ float xor_swz(float v) { return __int_as_float(__builtin_amdgcn_ds_swizzle(__float_as_int(v), (K << 10) | 0x1f)); }
; __device__ __forceinline__ float half_sum(float v) { auto rr = __builtin_amdgcn_permlane32_swap(__float_as_uint(v), __float_as_uint(v), false, false); return __uint_as_float(rr[0]) + __uint_as_float(rr[1]); }
; __device__ __forceinline__ float bf_lo(unsigned w) { return __uint_as_float(w << 16); }
; __device__ __forceinline__ float bf_hi(unsigned w) { return __uint_as_float(w & 0xffff0000u); }
; __device__ __forceinline__ u32x4 pack8(const f32x4 a, const f32x4 b) { u32x4 w; w.x = cvt_pk_bf16(a[0], a[1]); w.y = cvt_pk_bf16(a[2], a[3]); w.z = cvt_pk_bf16(b[0], b[1]); w.w = cvt_pk_bf16(b[2], b[3]); return w; }
;     __device__ __forceinline__ void operator()(const f32x4 (&acc)[2][2][4][2], const Unit& u, int wr, int wc, int fr, int fq) const {
;         const int row0 = u.pm * BM + wr * 64 + fr, col0 = u.pn * BM + wc * 32 + 8 * fq;
; #pragma unroll
;         for (int ai = 0; ai < 2; ++ai)
; #pragma unroll
;             for (int m = 0; m < 4; ++m) {
;                 const size_t row = (size_t)(row0 + ai * HALF + m * 16); float s = 0.f;
; #pragma unroll
;                 for (int bj = 0; bj < 2; ++bj) {
;                     const size_t off = row * 1024 + col0 + bj * HALF;
;                     const u32x4 w = __builtin_nontemporal_load((const u32x4*)(xb + off));
;                     const f32x4 r0 = (f32x4){bf_lo(w.x), bf_hi(w.x), bf_lo(w.y), bf_hi(w.y)} + acc[ai][bj][m][0], r1 = (f32x4){bf_lo(w.z), bf_hi(w.z), bf_lo(w.w), bf_hi(w.w)} + acc[ai][bj][m][1];
;                     __builtin_nontemporal_store(pack8(r0, r1), (u32x4*)(xb + off));
;                     s += (r0[0] * r0[0] + r0[1] * r0[1]) + (r0[2] * r0[2] + r0[3] * r0[3]) + (r1[0] * r1[0] + r1[1] * r1[1]) + (r1[2] * r1[2] + r1[3] * r1[3]);
;                 }
;                 s += xor_swz<16>(s); s = half_sum(s);
;                 if (fq == 0) ssq[row * 16 + u.pn * 4 + wc] = s;
;             }
;     }
.LBB0_504:
	v_lshl_add_u32 v146, s24, 8, v148
	v_ashrrev_i32_e32 v147, 31, v146
	v_lshl_or_b32 v144, s6, 8, v150
	v_lshlrev_b64 v[154:155], 11, v[146:147]
	v_ashrrev_i32_e32 v145, 31, v144
	v_lshl_add_u64 v[154:155], s[46:47], 0, v[154:155]
	v_lshl_add_u64 v[158:159], v[144:145], 1, v[154:155]
	global_load_dwordx4 v[154:157], v[158:159], off nt
	s_lshl_b32 s24, s6, 2
	s_ashr_i32 s25, s24, 31
	s_waitcnt vmcnt(0)
	v_lshlrev_b32_e32 v160, 16, v154
	v_and_b32_e32 v161, 0xffff0000, v154
	v_lshlrev_b32_e32 v154, 16, v155
	v_and_b32_e32 v155, 0xffff0000, v155
	v_lshlrev_b32_e32 v162, 16, v156
	v_and_b32_e32 v163, 0xffff0000, v156
	v_lshlrev_b32_e32 v156, 16, v157
	v_and_b32_e32 v157, 0xffff0000, v157
	v_pk_add_f32 v[154:155], v[126:127], v[154:155]
	v_pk_add_f32 v[160:161], v[124:125], v[160:161]
	v_pk_add_f32 v[156:157], v[122:123], v[156:157]
	v_pk_add_f32 v[162:163], v[120:121], v[162:163]
	v_cvt_pk_bf16_f32 v120, v160, v161
	v_cvt_pk_bf16_f32 v121, v154, v155
	v_mul_f32_e32 v161, v161, v161
	v_cvt_pk_bf16_f32 v122, v162, v163
	v_cvt_pk_bf16_f32 v123, v156, v157
	global_load_dwordx4 v[124:127], v[158:159], off offset:256 nt
	v_mul_f32_e32 v155, v155, v155
	v_mul_f32_e32 v163, v163, v163
	v_fmac_f32_e32 v161, v160, v160
	v_fmac_f32_e32 v155, v154, v154
	v_mul_f32_e32 v157, v157, v157
	global_store_dwordx4 v[158:159], v[120:123], off
	v_fmac_f32_e32 v163, v162, v162
	v_fmac_f32_e32 v157, v156, v156
	v_add_f32_e32 v120, v161, v155
	v_add_f32_e32 v120, v163, v120
	v_add_f32_e32 v154, v157, v120
	s_waitcnt vmcnt(1)
	v_lshlrev_b32_e32 v120, 16, v124
	v_and_b32_e32 v121, 0xffff0000, v124
	v_lshlrev_b32_e32 v122, 16, v125
	v_and_b32_e32 v123, 0xffff0000, v125
	v_lshlrev_b32_e32 v124, 16, v126
	v_and_b32_e32 v125, 0xffff0000, v126
	v_lshlrev_b32_e32 v126, 16, v127
	v_and_b32_e32 v127, 0xffff0000, v127
	v_pk_add_f32 v[118:119], v[118:119], v[122:123]
	v_pk_add_f32 v[116:117], v[116:117], v[120:121]
	v_pk_add_f32 v[120:121], v[114:115], v[126:127]
	v_pk_add_f32 v[114:115], v[112:113], v[124:125]
	v_cvt_pk_bf16_f32 v112, v116, v117
	v_mul_f32_e32 v113, v117, v117
	v_mul_f32_e32 v117, v119, v119
	v_mul_f32_e32 v122, v115, v115
	v_fmac_f32_e32 v113, v116, v116
	v_fmac_f32_e32 v117, v118, v118
	v_mul_f32_e32 v123, v121, v121
	v_fmac_f32_e32 v122, v114, v114
	v_add_f32_e32 v113, v113, v117
	v_fmac_f32_e32 v123, v120, v120
	v_add_f32_e32 v113, v122, v113
	v_add_f32_e32 v113, v123, v113
	v_add_f32_e32 v116, v154, v113
	ds_swizzle_b32 v117, v116 offset:swizzle(SWAP,16)
	v_cvt_pk_bf16_f32 v113, v118, v119
	v_cvt_pk_bf16_f32 v114, v114, v115
	v_cvt_pk_bf16_f32 v115, v120, v121
	global_store_dwordx4 v[158:159], v[112:115], off offset:256
	s_waitcnt lgkmcnt(0)
	s_nop 0
	v_add_f32_e32 v112, v116, v117
	v_mov_b32_e32 v113, v112
	s_nop 1
	v_permlane32_swap_b32_e32 v112, v113
	s_and_saveexec_b64 s[26:27], s[2:3]
	s_cbranch_execz .LBB0_506
	v_add_f32_e32 v114, v112, v113
	v_lshlrev_b64 v[112:113], 6, v[146:147]
	v_lshl_add_u64 v[112:113], s[10:11], 0, v[112:113]
	v_lshl_add_u64 v[112:113], s[24:25], 2, v[112:113]
	s_lshl_b32 s6, s38, 2
	v_lshl_add_u64 v[112:113], v[112:113], 0, s[6:7]
	global_store_dword v[112:113], v114, off
.LBB0_506:
	s_or_b64 exec, exec, s[26:27]
	v_or_b32_e32 v112, 16, v146
	v_ashrrev_i32_e32 v113, 31, v112
	v_lshlrev_b64 v[114:115], 11, v[112:113]
	v_lshl_add_u64 v[114:115], s[46:47], 0, v[114:115]
	v_lshl_add_u64 v[118:119], v[144:145], 1, v[114:115]
	global_load_dwordx4 v[114:117], v[118:119], off nt
	s_waitcnt vmcnt(0)
	v_lshlrev_b32_e32 v120, 16, v114
	v_and_b32_e32 v121, 0xffff0000, v114
	v_lshlrev_b32_e32 v114, 16, v115
	v_and_b32_e32 v115, 0xffff0000, v115
	v_lshlrev_b32_e32 v122, 16, v116
	v_and_b32_e32 v123, 0xffff0000, v116
	v_lshlrev_b32_e32 v116, 16, v117
	v_and_b32_e32 v117, 0xffff0000, v117
	v_pk_add_f32 v[114:115], v[110:111], v[114:115]
	v_pk_add_f32 v[120:121], v[108:109], v[120:121]
	v_pk_add_f32 v[116:117], v[106:107], v[116:117]
	v_pk_add_f32 v[122:123], v[104:105], v[122:123]
	v_cvt_pk_bf16_f32 v104, v120, v121
	v_cvt_pk_bf16_f32 v105, v114, v115
	v_mul_f32_e32 v121, v121, v121
	v_cvt_pk_bf16_f32 v106, v122, v123
	v_cvt_pk_bf16_f32 v107, v116, v117
	global_load_dwordx4 v[108:111], v[118:119], off offset:256 nt
	v_mul_f32_e32 v115, v115, v115
	v_mul_f32_e32 v123, v123, v123
	v_fmac_f32_e32 v121, v120, v120
	v_fmac_f32_e32 v115, v114, v114
	v_mul_f32_e32 v117, v117, v117
	global_store_dwordx4 v[118:119], v[104:107], off
	v_fmac_f32_e32 v123, v122, v122
	v_fmac_f32_e32 v117, v116, v116
	v_add_f32_e32 v104, v121, v115
	v_add_f32_e32 v104, v123, v104
	v_add_f32_e32 v114, v117, v104
	s_waitcnt vmcnt(1)
	v_lshlrev_b32_e32 v104, 16, v108
	v_and_b32_e32 v105, 0xffff0000, v108
	v_lshlrev_b32_e32 v106, 16, v109
	v_and_b32_e32 v107, 0xffff0000, v109
	v_lshlrev_b32_e32 v108, 16, v110
	v_and_b32_e32 v109, 0xffff0000, v110
	v_lshlrev_b32_e32 v110, 16, v111
	v_and_b32_e32 v111, 0xffff0000, v111
	v_pk_add_f32 v[102:103], v[102:103], v[106:107]
	v_pk_add_f32 v[100:101], v[100:101], v[104:105]
	v_pk_add_f32 v[104:105], v[98:99], v[110:111]
	v_pk_add_f32 v[98:99], v[96:97], v[108:109]
	v_cvt_pk_bf16_f32 v96, v100, v101
	v_mul_f32_e32 v97, v101, v101
	v_mul_f32_e32 v101, v103, v103
	v_mul_f32_e32 v106, v99, v99
	v_fmac_f32_e32 v97, v100, v100
	v_fmac_f32_e32 v101, v102, v102
	v_mul_f32_e32 v107, v105, v105
	v_fmac_f32_e32 v106, v98, v98
	v_add_f32_e32 v97, v97, v101
	v_fmac_f32_e32 v107, v104, v104
	v_add_f32_e32 v97, v106, v97
	v_add_f32_e32 v97, v107, v97
	v_add_f32_e32 v100, v114, v97
	ds_swizzle_b32 v101, v100 offset:swizzle(SWAP,16)
	v_cvt_pk_bf16_f32 v97, v102, v103
	v_cvt_pk_bf16_f32 v98, v98, v99
	v_cvt_pk_bf16_f32 v99, v104, v105
	global_store_dwordx4 v[118:119], v[96:99], off offset:256
	s_waitcnt lgkmcnt(0)
	s_nop 0
	v_add_f32_e32 v96, v100, v101
	v_mov_b32_e32 v97, v96
	s_nop 1
	v_permlane32_swap_b32_e32 v96, v97
	s_and_saveexec_b64 s[26:27], s[2:3]
	s_cbranch_execz .LBB0_508
	v_add_f32_e32 v98, v96, v97
	v_lshlrev_b64 v[96:97], 6, v[112:113]
	v_lshl_add_u64 v[96:97], s[10:11], 0, v[96:97]
	v_lshl_add_u64 v[96:97], s[24:25], 2, v[96:97]
	s_lshl_b32 s6, s38, 2
	v_lshl_add_u64 v[96:97], v[96:97], 0, s[6:7]
	global_store_dword v[96:97], v98, off
; template <int K> __device__ __forceinline__ float xor_swz(float v) { return __int_as_float(__builtin_amdgcn_ds_swizzle(__float_as_int(v), (K << 10) | 0x1f)); }
; __device__ __forceinline__ float half_sum(float v) { auto rr = __builtin_amdgcn_permlane32_swap(__float_as_uint(v), __float_as_uint(v), false, false); return __uint_as_float(rr[0]) + __uint_as_float(rr[1]); }
; __device__ __forceinline__ float bf_lo(unsigned w) { return __uint_as_float(w << 16); }
; __device__ __forceinline__ float bf_hi(unsigned w) { return __uint_as_float(w & 0xffff0000u); }
; __device__ __forceinline__ u32x4 pack8(const f32x4 a, const f32x4 b) { u32x4 w; w.x = cvt_pk_bf16(a[0], a[1]); w.y = cvt_pk_bf16(a[2], a[3]); w.z = cvt_pk_bf16(b[0], b[1]); w.w = cvt_pk_bf16(b[2], b[3]); return w; }
;     __device__ __forceinline__ void operator()(const f32x4 (&acc)[2][2][4][2], const Unit& u, int wr, int wc, int fr, int fq) const {
;         const int row0 = u.pm * BM + wr * 64 + fr, col0 = u.pn * BM + wc * 32 + 8 * fq;
; #pragma unroll
;         for (int ai = 0; ai < 2; ++ai)
; #pragma unroll
;             for (int m = 0; m < 4; ++m) {
;                 const size_t row = (size_t)(row0 + ai * HALF + m * 16); float s = 0.f;
; #pragma unroll
;                 for (int bj = 0; bj < 2; ++bj) {
;                     const size_t off = row * 1024 + col0 + bj * HALF;
;                     const u32x4 w = __builtin_nontemporal_load((const u32x4*)(xb + off));
;                     const f32x4 r0 = (f32x4){bf_lo(w.x), bf_hi(w.x), bf_lo(w.y), bf_hi(w.y)} + acc[ai][bj][m][0], r1 = (f32x4){bf_lo(w.z), bf_hi(w.z), bf_lo(w.w), bf_hi(w.w)} + acc[ai][bj][m][1];
;                     __builtin_nontemporal_store(pack8(r0, r1), (u32x4*)(xb + off));
;                     s += (r0[0] * r0[0] + r0[1] * r0[1]) + (r0[2] * r0[2] + r0[3] * r0[3]) + (r1[0] * r1[0] + r1[1] * r1[1]) + (r1[2] * r1[2] + r1[3] * r1[3]);
;                 }
;                 s += xor_swz<16>(s); s = half_sum(s);
;                 if (fq == 0) ssq[row * 16 + u.pn * 4 + wc] = s;
;             }
;     }
.LBB0_508:
	s_or_b64 exec, exec, s[26:27]
	v_or_b32_e32 v96, 32, v146
	v_ashrrev_i32_e32 v97, 31, v96
	v_lshlrev_b64 v[98:99], 11, v[96:97]
	v_lshl_add_u64 v[98:99], s[46:47], 0, v[98:99]
	v_lshl_add_u64 v[102:103], v[144:145], 1, v[98:99]
	global_load_dwordx4 v[98:101], v[102:103], off nt
	s_waitcnt vmcnt(0)
	v_lshlrev_b32_e32 v104, 16, v98
	v_and_b32_e32 v105, 0xffff0000, v98
	v_lshlrev_b32_e32 v98, 16, v99
	v_and_b32_e32 v99, 0xffff0000, v99
	v_lshlrev_b32_e32 v106, 16, v100
	v_and_b32_e32 v107, 0xffff0000, v100
	v_lshlrev_b32_e32 v100, 16, v101
	v_and_b32_e32 v101, 0xffff0000, v101
	v_pk_add_f32 v[98:99], v[94:95], v[98:99]
	v_pk_add_f32 v[104:105], v[92:93], v[104:105]
	v_pk_add_f32 v[100:101], v[90:91], v[100:101]
	v_pk_add_f32 v[106:107], v[88:89], v[106:107]
	v_cvt_pk_bf16_f32 v88, v104, v105
	v_cvt_pk_bf16_f32 v89, v98, v99
	v_mul_f32_e32 v105, v105, v105
	v_cvt_pk_bf16_f32 v90, v106, v107
	v_cvt_pk_bf16_f32 v91, v100, v101
	global_load_dwordx4 v[92:95], v[102:103], off offset:256 nt
	v_mul_f32_e32 v99, v99, v99
	v_mul_f32_e32 v107, v107, v107
	v_fmac_f32_e32 v105, v104, v104
	v_fmac_f32_e32 v99, v98, v98
	v_mul_f32_e32 v101, v101, v101
	global_store_dwordx4 v[102:103], v[88:91], off
	v_fmac_f32_e32 v107, v106, v106
	v_fmac_f32_e32 v101, v100, v100
	v_add_f32_e32 v88, v105, v99
	v_add_f32_e32 v88, v107, v88
	v_add_f32_e32 v98, v101, v88
	s_waitcnt vmcnt(1)
	v_lshlrev_b32_e32 v88, 16, v92
	v_and_b32_e32 v89, 0xffff0000, v92
	v_lshlrev_b32_e32 v90, 16, v93
	v_and_b32_e32 v91, 0xffff0000, v93
	v_lshlrev_b32_e32 v92, 16, v94
	v_and_b32_e32 v93, 0xffff0000, v94
	v_lshlrev_b32_e32 v94, 16, v95
	v_and_b32_e32 v95, 0xffff0000, v95
	v_pk_add_f32 v[86:87], v[86:87], v[90:91]
	v_pk_add_f32 v[84:85], v[84:85], v[88:89]
	v_pk_add_f32 v[88:89], v[82:83], v[94:95]
	v_pk_add_f32 v[82:83], v[80:81], v[92:93]
	v_cvt_pk_bf16_f32 v80, v84, v85
	v_mul_f32_e32 v81, v85, v85
	v_mul_f32_e32 v85, v87, v87
	v_mul_f32_e32 v90, v83, v83
	v_fmac_f32_e32 v81, v84, v84
	v_fmac_f32_e32 v85, v86, v86
	v_mul_f32_e32 v91, v89, v89
	v_fmac_f32_e32 v90, v82, v82
	v_add_f32_e32 v81, v81, v85
	v_fmac_f32_e32 v91, v88, v88
	v_add_f32_e32 v81, v90, v81
	v_add_f32_e32 v81, v91, v81
	v_add_f32_e32 v84, v98, v81
	ds_swizzle_b32 v85, v84 offset:swizzle(SWAP,16)
	v_cvt_pk_bf16_f32 v81, v86, v87
	v_cvt_pk_bf16_f32 v82, v82, v83
	v_cvt_pk_bf16_f32 v83, v88, v89
	global_store_dwordx4 v[102:103], v[80:83], off offset:256
	s_waitcnt lgkmcnt(0)
	s_nop 0
	v_add_f32_e32 v80, v84, v85
	v_mov_b32_e32 v81, v80
	s_nop 1
	v_permlane32_swap_b32_e32 v80, v81
	s_and_saveexec_b64 s[26:27], s[2:3]
	s_cbranch_execz .LBB0_510
	v_add_f32_e32 v82, v80, v81
	v_lshlrev_b64 v[80:81], 6, v[96:97]
	v_lshl_add_u64 v[80:81], s[10:11], 0, v[80:81]
	v_lshl_add_u64 v[80:81], s[24:25], 2, v[80:81]
	s_lshl_b32 s6, s38, 2
	v_lshl_add_u64 v[80:81], v[80:81], 0, s[6:7]
	global_store_dword v[80:81], v82, off
.LBB0_510:
	s_or_b64 exec, exec, s[26:27]
	v_or_b32_e32 v80, 48, v146
	v_ashrrev_i32_e32 v81, 31, v80
	v_lshlrev_b64 v[82:83], 11, v[80:81]
	v_lshl_add_u64 v[82:83], s[46:47], 0, v[82:83]
	v_lshl_add_u64 v[86:87], v[144:145], 1, v[82:83]
	global_load_dwordx4 v[82:85], v[86:87], off nt
	s_waitcnt vmcnt(0)
	v_lshlrev_b32_e32 v88, 16, v82
	v_and_b32_e32 v89, 0xffff0000, v82
	v_lshlrev_b32_e32 v82, 16, v83
	v_and_b32_e32 v83, 0xffff0000, v83
	v_lshlrev_b32_e32 v90, 16, v84
	v_and_b32_e32 v91, 0xffff0000, v84
	v_lshlrev_b32_e32 v84, 16, v85
	v_and_b32_e32 v85, 0xffff0000, v85
	v_pk_add_f32 v[82:83], v[78:79], v[82:83]
	v_pk_add_f32 v[88:89], v[76:77], v[88:89]
	v_pk_add_f32 v[84:85], v[74:75], v[84:85]
	v_pk_add_f32 v[90:91], v[72:73], v[90:91]
	v_cvt_pk_bf16_f32 v72, v88, v89
	v_cvt_pk_bf16_f32 v73, v82, v83
	v_mul_f32_e32 v89, v89, v89
	v_cvt_pk_bf16_f32 v74, v90, v91
	v_cvt_pk_bf16_f32 v75, v84, v85
	global_load_dwordx4 v[76:79], v[86:87], off offset:256 nt
	v_mul_f32_e32 v83, v83, v83
	v_mul_f32_e32 v91, v91, v91
	v_fmac_f32_e32 v89, v88, v88
	v_fmac_f32_e32 v83, v82, v82
	v_mul_f32_e32 v85, v85, v85
	global_store_dwordx4 v[86:87], v[72:75], off
	v_fmac_f32_e32 v91, v90, v90
	v_fmac_f32_e32 v85, v84, v84
	v_add_f32_e32 v72, v89, v83
	v_add_f32_e32 v72, v91, v72
	v_add_f32_e32 v82, v85, v72
	s_waitcnt vmcnt(1)
	v_lshlrev_b32_e32 v72, 16, v76
	v_and_b32_e32 v73, 0xffff0000, v76
	v_lshlrev_b32_e32 v74, 16, v77
	v_and_b32_e32 v75, 0xffff0000, v77
	v_lshlrev_b32_e32 v76, 16, v78
	v_and_b32_e32 v77, 0xffff0000, v78
	v_lshlrev_b32_e32 v78, 16, v79
	v_and_b32_e32 v79, 0xffff0000, v79
	v_pk_add_f32 v[70:71], v[70:71], v[74:75]
	v_pk_add_f32 v[68:69], v[68:69], v[72:73]
	v_pk_add_f32 v[72:73], v[66:67], v[78:79]
	v_pk_add_f32 v[66:67], v[64:65], v[76:77]
	v_cvt_pk_bf16_f32 v64, v68, v69
	v_mul_f32_e32 v65, v69, v69
	v_mul_f32_e32 v69, v71, v71
	v_mul_f32_e32 v74, v67, v67
	v_fmac_f32_e32 v65, v68, v68
	v_fmac_f32_e32 v69, v70, v70
	v_mul_f32_e32 v75, v73, v73
	v_fmac_f32_e32 v74, v66, v66
	v_add_f32_e32 v65, v65, v69
	v_fmac_f32_e32 v75, v72, v72
	v_add_f32_e32 v65, v74, v65
	v_add_f32_e32 v65, v75, v65
	v_add_f32_e32 v68, v82, v65
	ds_swizzle_b32 v69, v68 offset:swizzle(SWAP,16)
	v_cvt_pk_bf16_f32 v65, v70, v71
	v_cvt_pk_bf16_f32 v66, v66, v67
	v_cvt_pk_bf16_f32 v67, v72, v73
	global_store_dwordx4 v[86:87], v[64:67], off offset:256
	s_waitcnt lgkmcnt(0)
	s_nop 0
	v_add_f32_e32 v64, v68, v69
	v_mov_b32_e32 v65, v64
	s_nop 1
	v_permlane32_swap_b32_e32 v64, v65
	s_and_saveexec_b64 s[26:27], s[2:3]
	s_cbranch_execz .LBB0_512
	v_add_f32_e32 v66, v64, v65
	v_lshlrev_b64 v[64:65], 6, v[80:81]
	v_lshl_add_u64 v[64:65], s[10:11], 0, v[64:65]
	v_lshl_add_u64 v[64:65], s[24:25], 2, v[64:65]
	s_lshl_b32 s6, s38, 2
	v_lshl_add_u64 v[64:65], v[64:65], 0, s[6:7]
	global_store_dword v[64:65], v66, off
; template <int K> __device__ __forceinline__ float xor_swz(float v) { return __int_as_float(__builtin_amdgcn_ds_swizzle(__float_as_int(v), (K << 10) | 0x1f)); }
; __device__ __forceinline__ float half_sum(float v) { auto rr = __builtin_amdgcn_permlane32_swap(__float_as_uint(v), __float_as_uint(v), false, false); return __uint_as_float(rr[0]) + __uint_as_float(rr[1]); }
; __device__ __forceinline__ float bf_lo(unsigned w) { return __uint_as_float(w << 16); }
; __device__ __forceinline__ float bf_hi(unsigned w) { return __uint_as_float(w & 0xffff0000u); }
; __device__ __forceinline__ u32x4 pack8(const f32x4 a, const f32x4 b) { u32x4 w; w.x = cvt_pk_bf16(a[0], a[1]); w.y = cvt_pk_bf16(a[2], a[3]); w.z = cvt_pk_bf16(b[0], b[1]); w.w = cvt_pk_bf16(b[2], b[3]); return w; }
;     __device__ __forceinline__ void operator()(const f32x4 (&acc)[2][2][4][2], const Unit& u, int wr, int wc, int fr, int fq) const {
;         const int row0 = u.pm * BM + wr * 64 + fr, col0 = u.pn * BM + wc * 32 + 8 * fq;
; #pragma unroll
;         for (int ai = 0; ai < 2; ++ai)
; #pragma unroll
;             for (int m = 0; m < 4; ++m) {
;                 const size_t row = (size_t)(row0 + ai * HALF + m * 16); float s = 0.f;
; #pragma unroll
;                 for (int bj = 0; bj < 2; ++bj) {
;                     const size_t off = row * 1024 + col0 + bj * HALF;
;                     const u32x4 w = __builtin_nontemporal_load((const u32x4*)(xb + off));
;                     const f32x4 r0 = (f32x4){bf_lo(w.x), bf_hi(w.x), bf_lo(w.y), bf_hi(w.y)} + acc[ai][bj][m][0], r1 = (f32x4){bf_lo(w.z), bf_hi(w.z), bf_lo(w.w), bf_hi(w.w)} + acc[ai][bj][m][1];
;                     __builtin_nontemporal_store(pack8(r0, r1), (u32x4*)(xb + off));
;                     s += (r0[0] * r0[0] + r0[1] * r0[1]) + (r0[2] * r0[2] + r0[3] * r0[3]) + (r1[0] * r1[0] + r1[1] * r1[1]) + (r1[2] * r1[2] + r1[3] * r1[3]);
;                 }
;                 s += xor_swz<16>(s); s = half_sum(s);
;                 if (fq == 0) ssq[row * 16 + u.pn * 4 + wc] = s;
;             }
;     }
.LBB0_512:
	s_or_b64 exec, exec, s[26:27]
	v_add_u32_e32 v64, 0x80, v146
	v_ashrrev_i32_e32 v65, 31, v64
	v_lshlrev_b64 v[66:67], 11, v[64:65]
	v_lshl_add_u64 v[66:67], s[46:47], 0, v[66:67]
	v_lshl_add_u64 v[70:71], v[144:145], 1, v[66:67]
	global_load_dwordx4 v[66:69], v[70:71], off nt
	s_waitcnt vmcnt(0)
	v_lshlrev_b32_e32 v72, 16, v66
	v_and_b32_e32 v73, 0xffff0000, v66
	v_lshlrev_b32_e32 v66, 16, v67
	v_and_b32_e32 v67, 0xffff0000, v67
	v_lshlrev_b32_e32 v74, 16, v68
	v_and_b32_e32 v75, 0xffff0000, v68
	v_lshlrev_b32_e32 v68, 16, v69
	v_and_b32_e32 v69, 0xffff0000, v69
	v_pk_add_f32 v[66:67], v[62:63], v[66:67]
	v_pk_add_f32 v[72:73], v[60:61], v[72:73]
	v_pk_add_f32 v[68:69], v[58:59], v[68:69]
	v_pk_add_f32 v[74:75], v[56:57], v[74:75]
	v_cvt_pk_bf16_f32 v56, v72, v73
	v_cvt_pk_bf16_f32 v57, v66, v67
	v_mul_f32_e32 v73, v73, v73
	v_cvt_pk_bf16_f32 v58, v74, v75
	v_cvt_pk_bf16_f32 v59, v68, v69
	global_load_dwordx4 v[60:63], v[70:71], off offset:256 nt
	v_mul_f32_e32 v67, v67, v67
	v_mul_f32_e32 v75, v75, v75
	v_fmac_f32_e32 v73, v72, v72
	v_fmac_f32_e32 v67, v66, v66
	v_mul_f32_e32 v69, v69, v69
	global_store_dwordx4 v[70:71], v[56:59], off
	v_fmac_f32_e32 v75, v74, v74
	v_fmac_f32_e32 v69, v68, v68
	v_add_f32_e32 v56, v73, v67
	v_add_f32_e32 v56, v75, v56
	v_add_f32_e32 v66, v69, v56
	s_waitcnt vmcnt(1)
	v_lshlrev_b32_e32 v56, 16, v60
	v_and_b32_e32 v57, 0xffff0000, v60
	v_lshlrev_b32_e32 v58, 16, v61
	v_and_b32_e32 v59, 0xffff0000, v61
	v_lshlrev_b32_e32 v60, 16, v62
	v_and_b32_e32 v61, 0xffff0000, v62
	v_lshlrev_b32_e32 v62, 16, v63
	v_and_b32_e32 v63, 0xffff0000, v63
	v_pk_add_f32 v[54:55], v[54:55], v[58:59]
	v_pk_add_f32 v[52:53], v[52:53], v[56:57]
	v_pk_add_f32 v[56:57], v[50:51], v[62:63]
	v_pk_add_f32 v[50:51], v[48:49], v[60:61]
	v_cvt_pk_bf16_f32 v48, v52, v53
	v_mul_f32_e32 v49, v53, v53
	v_mul_f32_e32 v53, v55, v55
	v_mul_f32_e32 v58, v51, v51
	v_fmac_f32_e32 v49, v52, v52
	v_fmac_f32_e32 v53, v54, v54
	v_mul_f32_e32 v59, v57, v57
	v_fmac_f32_e32 v58, v50, v50
	v_add_f32_e32 v49, v49, v53
	v_fmac_f32_e32 v59, v56, v56
	v_add_f32_e32 v49, v58, v49
	v_add_f32_e32 v49, v59, v49
	v_add_f32_e32 v52, v66, v49
	ds_swizzle_b32 v53, v52 offset:swizzle(SWAP,16)
	v_cvt_pk_bf16_f32 v49, v54, v55
	v_cvt_pk_bf16_f32 v50, v50, v51
	v_cvt_pk_bf16_f32 v51, v56, v57
	global_store_dwordx4 v[70:71], v[48:51], off offset:256
	s_waitcnt lgkmcnt(0)
	s_nop 0
	v_add_f32_e32 v48, v52, v53
	v_mov_b32_e32 v49, v48
	s_nop 1
	v_permlane32_swap_b32_e32 v48, v49
	s_and_saveexec_b64 s[26:27], s[2:3]
	s_cbranch_execz .LBB0_514
	v_add_f32_e32 v50, v48, v49
	v_lshlrev_b64 v[48:49], 6, v[64:65]
	v_lshl_add_u64 v[48:49], s[10:11], 0, v[48:49]
	v_lshl_add_u64 v[48:49], s[24:25], 2, v[48:49]
	s_lshl_b32 s6, s38, 2
	v_lshl_add_u64 v[48:49], v[48:49], 0, s[6:7]
	global_store_dword v[48:49], v50, off
.LBB0_514:
	s_or_b64 exec, exec, s[26:27]
	v_add_u32_e32 v48, 0x90, v146
	v_ashrrev_i32_e32 v49, 31, v48
	v_lshlrev_b64 v[50:51], 11, v[48:49]
	v_lshl_add_u64 v[50:51], s[46:47], 0, v[50:51]
	v_lshl_add_u64 v[54:55], v[144:145], 1, v[50:51]
	global_load_dwordx4 v[50:53], v[54:55], off nt
	s_waitcnt vmcnt(0)
	v_lshlrev_b32_e32 v56, 16, v50
	v_and_b32_e32 v57, 0xffff0000, v50
	v_lshlrev_b32_e32 v50, 16, v51
	v_and_b32_e32 v51, 0xffff0000, v51
	v_lshlrev_b32_e32 v58, 16, v52
	v_and_b32_e32 v59, 0xffff0000, v52
	v_lshlrev_b32_e32 v52, 16, v53
	v_and_b32_e32 v53, 0xffff0000, v53
	v_pk_add_f32 v[50:51], v[46:47], v[50:51]
	v_pk_add_f32 v[56:57], v[44:45], v[56:57]
	v_pk_add_f32 v[52:53], v[42:43], v[52:53]
	v_pk_add_f32 v[58:59], v[40:41], v[58:59]
	v_cvt_pk_bf16_f32 v40, v56, v57
	v_cvt_pk_bf16_f32 v41, v50, v51
	v_mul_f32_e32 v57, v57, v57
	v_cvt_pk_bf16_f32 v42, v58, v59
	v_cvt_pk_bf16_f32 v43, v52, v53
	global_load_dwordx4 v[44:47], v[54:55], off offset:256 nt
	v_mul_f32_e32 v51, v51, v51
	v_mul_f32_e32 v59, v59, v59
	v_fmac_f32_e32 v57, v56, v56
	v_fmac_f32_e32 v51, v50, v50
	v_mul_f32_e32 v53, v53, v53
	global_store_dwordx4 v[54:55], v[40:43], off
	v_fmac_f32_e32 v59, v58, v58
	v_fmac_f32_e32 v53, v52, v52
	v_add_f32_e32 v40, v57, v51
	v_add_f32_e32 v40, v59, v40
	v_add_f32_e32 v50, v53, v40
	s_waitcnt vmcnt(1)
	v_lshlrev_b32_e32 v40, 16, v44
	v_and_b32_e32 v41, 0xffff0000, v44
	v_lshlrev_b32_e32 v42, 16, v45
	v_and_b32_e32 v43, 0xffff0000, v45
	v_lshlrev_b32_e32 v44, 16, v46
	v_and_b32_e32 v45, 0xffff0000, v46
	v_lshlrev_b32_e32 v46, 16, v47
	v_and_b32_e32 v47, 0xffff0000, v47
	v_pk_add_f32 v[38:39], v[38:39], v[42:43]
	v_pk_add_f32 v[36:37], v[36:37], v[40:41]
	v_pk_add_f32 v[40:41], v[34:35], v[46:47]
	v_pk_add_f32 v[34:35], v[32:33], v[44:45]
	v_cvt_pk_bf16_f32 v32, v36, v37
	v_mul_f32_e32 v33, v37, v37
	v_mul_f32_e32 v37, v39, v39
	v_mul_f32_e32 v42, v35, v35
	v_fmac_f32_e32 v33, v36, v36
	v_fmac_f32_e32 v37, v38, v38
	v_mul_f32_e32 v43, v41, v41
	v_fmac_f32_e32 v42, v34, v34
	v_add_f32_e32 v33, v33, v37
	v_fmac_f32_e32 v43, v40, v40
	v_add_f32_e32 v33, v42, v33
	v_add_f32_e32 v33, v43, v33
	v_add_f32_e32 v36, v50, v33
	ds_swizzle_b32 v37, v36 offset:swizzle(SWAP,16)
	v_cvt_pk_bf16_f32 v33, v38, v39
	v_cvt_pk_bf16_f32 v34, v34, v35
	v_cvt_pk_bf16_f32 v35, v40, v41
	global_store_dwordx4 v[54:55], v[32:35], off offset:256
	s_waitcnt lgkmcnt(0)
	s_nop 0
	v_add_f32_e32 v32, v36, v37
	v_mov_b32_e32 v33, v32
	s_nop 1
	v_permlane32_swap_b32_e32 v32, v33
	s_and_saveexec_b64 s[26:27], s[2:3]
	s_cbranch_execz .LBB0_516
	v_add_f32_e32 v34, v32, v33
	v_lshlrev_b64 v[32:33], 6, v[48:49]
	v_lshl_add_u64 v[32:33], s[10:11], 0, v[32:33]
	v_lshl_add_u64 v[32:33], s[24:25], 2, v[32:33]
	s_lshl_b32 s6, s38, 2
	v_lshl_add_u64 v[32:33], v[32:33], 0, s[6:7]
	global_store_dword v[32:33], v34, off
; template <int K> __device__ __forceinline__ float xor_swz(float v) { return __int_as_float(__builtin_amdgcn_ds_swizzle(__float_as_int(v), (K << 10) | 0x1f)); }
; __device__ __forceinline__ float half_sum(float v) { auto rr = __builtin_amdgcn_permlane32_swap(__float_as_uint(v), __float_as_uint(v), false, false); return __uint_as_float(rr[0]) + __uint_as_float(rr[1]); }
; __device__ __forceinline__ float bf_lo(unsigned w) { return __uint_as_float(w << 16); }
; __device__ __forceinline__ float bf_hi(unsigned w) { return __uint_as_float(w & 0xffff0000u); }
; __device__ __forceinline__ u32x4 pack8(const f32x4 a, const f32x4 b) { u32x4 w; w.x = cvt_pk_bf16(a[0], a[1]); w.y = cvt_pk_bf16(a[2], a[3]); w.z = cvt_pk_bf16(b[0], b[1]); w.w = cvt_pk_bf16(b[2], b[3]); return w; }
;     __device__ __forceinline__ void operator()(const f32x4 (&acc)[2][2][4][2], const Unit& u, int wr, int wc, int fr, int fq) const {
;         const int row0 = u.pm * BM + wr * 64 + fr, col0 = u.pn * BM + wc * 32 + 8 * fq;
; #pragma unroll
;         for (int ai = 0; ai < 2; ++ai)
; #pragma unroll
;             for (int m = 0; m < 4; ++m) {
;                 const size_t row = (size_t)(row0 + ai * HALF + m * 16); float s = 0.f;
; #pragma unroll
;                 for (int bj = 0; bj < 2; ++bj) {
;                     const size_t off = row * 1024 + col0 + bj * HALF;
;                     const u32x4 w = __builtin_nontemporal_load((const u32x4*)(xb + off));
;                     const f32x4 r0 = (f32x4){bf_lo(w.x), bf_hi(w.x), bf_lo(w.y), bf_hi(w.y)} + acc[ai][bj][m][0], r1 = (f32x4){bf_lo(w.z), bf_hi(w.z), bf_lo(w.w), bf_hi(w.w)} + acc[ai][bj][m][1];
;                     __builtin_nontemporal_store(pack8(r0, r1), (u32x4*)(xb + off));
;                     s += (r0[0] * r0[0] + r0[1] * r0[1]) + (r0[2] * r0[2] + r0[3] * r0[3]) + (r1[0] * r1[0] + r1[1] * r1[1]) + (r1[2] * r1[2] + r1[3] * r1[3]);
;                 }
;                 s += xor_swz<16>(s); s = half_sum(s);
;                 if (fq == 0) ssq[row * 16 + u.pn * 4 + wc] = s;
;             }
;     }
.LBB0_516:
	s_or_b64 exec, exec, s[26:27]
	v_add_u32_e32 v32, 0xa0, v146
	v_ashrrev_i32_e32 v33, 31, v32
	v_lshlrev_b64 v[34:35], 11, v[32:33]
	v_lshl_add_u64 v[34:35], s[46:47], 0, v[34:35]
	v_lshl_add_u64 v[38:39], v[144:145], 1, v[34:35]
	global_load_dwordx4 v[34:37], v[38:39], off nt
	s_waitcnt vmcnt(0)
	v_lshlrev_b32_e32 v40, 16, v34
	v_and_b32_e32 v41, 0xffff0000, v34
	v_lshlrev_b32_e32 v34, 16, v35
	v_and_b32_e32 v35, 0xffff0000, v35
	v_lshlrev_b32_e32 v42, 16, v36
	v_and_b32_e32 v43, 0xffff0000, v36
	v_lshlrev_b32_e32 v36, 16, v37
	v_and_b32_e32 v37, 0xffff0000, v37
	v_pk_add_f32 v[34:35], v[30:31], v[34:35]
	v_pk_add_f32 v[40:41], v[28:29], v[40:41]
	v_pk_add_f32 v[36:37], v[26:27], v[36:37]
	v_pk_add_f32 v[42:43], v[24:25], v[42:43]
	v_cvt_pk_bf16_f32 v24, v40, v41
	v_cvt_pk_bf16_f32 v25, v34, v35
	v_mul_f32_e32 v41, v41, v41
	v_cvt_pk_bf16_f32 v26, v42, v43
	v_cvt_pk_bf16_f32 v27, v36, v37
	global_load_dwordx4 v[28:31], v[38:39], off offset:256 nt
	v_mul_f32_e32 v35, v35, v35
	v_mul_f32_e32 v43, v43, v43
	v_fmac_f32_e32 v41, v40, v40
	v_fmac_f32_e32 v35, v34, v34
	v_mul_f32_e32 v37, v37, v37
	global_store_dwordx4 v[38:39], v[24:27], off
	v_fmac_f32_e32 v43, v42, v42
	v_fmac_f32_e32 v37, v36, v36
	v_add_f32_e32 v24, v41, v35
	v_add_f32_e32 v24, v43, v24
	v_add_f32_e32 v34, v37, v24
	s_waitcnt vmcnt(1)
	v_lshlrev_b32_e32 v24, 16, v28
	v_and_b32_e32 v25, 0xffff0000, v28
	v_lshlrev_b32_e32 v26, 16, v29
	v_and_b32_e32 v27, 0xffff0000, v29
	v_lshlrev_b32_e32 v28, 16, v30
	v_and_b32_e32 v29, 0xffff0000, v30
	v_lshlrev_b32_e32 v30, 16, v31
	v_and_b32_e32 v31, 0xffff0000, v31
	v_pk_add_f32 v[22:23], v[22:23], v[26:27]
	v_pk_add_f32 v[20:21], v[20:21], v[24:25]
	v_pk_add_f32 v[24:25], v[18:19], v[30:31]
	v_pk_add_f32 v[18:19], v[16:17], v[28:29]
	v_cvt_pk_bf16_f32 v16, v20, v21
	v_mul_f32_e32 v17, v21, v21
	v_mul_f32_e32 v21, v23, v23
	v_mul_f32_e32 v26, v19, v19
	v_fmac_f32_e32 v17, v20, v20
	v_fmac_f32_e32 v21, v22, v22
	v_mul_f32_e32 v27, v25, v25
	v_fmac_f32_e32 v26, v18, v18
	v_add_f32_e32 v17, v17, v21
	v_fmac_f32_e32 v27, v24, v24
	v_add_f32_e32 v17, v26, v17
	v_add_f32_e32 v17, v27, v17
	v_add_f32_e32 v20, v34, v17
	ds_swizzle_b32 v21, v20 offset:swizzle(SWAP,16)
	v_cvt_pk_bf16_f32 v17, v22, v23
	v_cvt_pk_bf16_f32 v18, v18, v19
	v_cvt_pk_bf16_f32 v19, v24, v25
	global_store_dwordx4 v[38:39], v[16:19], off offset:256
	s_waitcnt lgkmcnt(0)
	s_nop 0
	v_add_f32_e32 v16, v20, v21
	v_mov_b32_e32 v17, v16
	s_nop 1
	v_permlane32_swap_b32_e32 v16, v17
	s_and_saveexec_b64 s[26:27], s[2:3]
	s_cbranch_execz .LBB0_518
	v_add_f32_e32 v18, v16, v17
	v_lshlrev_b64 v[16:17], 6, v[32:33]
	v_lshl_add_u64 v[16:17], s[10:11], 0, v[16:17]
	v_lshl_add_u64 v[16:17], s[24:25], 2, v[16:17]
	s_lshl_b32 s6, s38, 2
	v_lshl_add_u64 v[16:17], v[16:17], 0, s[6:7]
	global_store_dword v[16:17], v18, off
.LBB0_518:
	s_or_b64 exec, exec, s[26:27]
	v_add_u32_e32 v16, 0xb0, v146
	v_ashrrev_i32_e32 v17, 31, v16
	v_lshlrev_b64 v[18:19], 11, v[16:17]
	v_lshl_add_u64 v[18:19], s[46:47], 0, v[18:19]
	v_lshl_add_u64 v[22:23], v[144:145], 1, v[18:19]
	global_load_dwordx4 v[18:21], v[22:23], off nt
	s_waitcnt vmcnt(0)
	v_lshlrev_b32_e32 v24, 16, v18
	v_and_b32_e32 v25, 0xffff0000, v18
	v_lshlrev_b32_e32 v18, 16, v19
	v_and_b32_e32 v19, 0xffff0000, v19
	v_lshlrev_b32_e32 v26, 16, v20
	v_and_b32_e32 v27, 0xffff0000, v20
	v_lshlrev_b32_e32 v20, 16, v21
	v_and_b32_e32 v21, 0xffff0000, v21
	v_pk_add_f32 v[18:19], v[14:15], v[18:19]
	v_pk_add_f32 v[24:25], v[12:13], v[24:25]
	v_pk_add_f32 v[20:21], v[10:11], v[20:21]
	v_pk_add_f32 v[26:27], v[8:9], v[26:27]
	v_cvt_pk_bf16_f32 v8, v24, v25
	v_cvt_pk_bf16_f32 v9, v18, v19
	v_mul_f32_e32 v25, v25, v25
	v_cvt_pk_bf16_f32 v10, v26, v27
	v_cvt_pk_bf16_f32 v11, v20, v21
	global_load_dwordx4 v[12:15], v[22:23], off offset:256 nt
	v_mul_f32_e32 v19, v19, v19
	v_mul_f32_e32 v27, v27, v27
	v_fmac_f32_e32 v25, v24, v24
	v_fmac_f32_e32 v19, v18, v18
	v_mul_f32_e32 v21, v21, v21
	global_store_dwordx4 v[22:23], v[8:11], off
	v_fmac_f32_e32 v27, v26, v26
	v_fmac_f32_e32 v21, v20, v20
	v_add_f32_e32 v8, v25, v19
	v_add_f32_e32 v8, v27, v8
	v_add_f32_e32 v18, v21, v8
	s_waitcnt vmcnt(1)
	v_lshlrev_b32_e32 v8, 16, v12
	v_and_b32_e32 v9, 0xffff0000, v12
	v_lshlrev_b32_e32 v10, 16, v13
	v_and_b32_e32 v11, 0xffff0000, v13
	v_lshlrev_b32_e32 v12, 16, v14
	v_and_b32_e32 v13, 0xffff0000, v14
	v_lshlrev_b32_e32 v14, 16, v15
	v_and_b32_e32 v15, 0xffff0000, v15
	v_pk_add_f32 v[6:7], v[6:7], v[10:11]
	v_pk_add_f32 v[4:5], v[4:5], v[8:9]
	v_pk_add_f32 v[8:9], v[2:3], v[14:15]
	v_pk_add_f32 v[2:3], v[0:1], v[12:13]
	v_cvt_pk_bf16_f32 v0, v4, v5
	v_mul_f32_e32 v1, v5, v5
	v_mul_f32_e32 v5, v7, v7
	v_mul_f32_e32 v10, v3, v3
	v_fmac_f32_e32 v1, v4, v4
	v_fmac_f32_e32 v5, v6, v6
	v_mul_f32_e32 v11, v9, v9
	v_fmac_f32_e32 v10, v2, v2
	v_add_f32_e32 v1, v1, v5
	v_fmac_f32_e32 v11, v8, v8
	v_add_f32_e32 v1, v10, v1
	v_add_f32_e32 v1, v11, v1
	v_add_f32_e32 v4, v18, v1
	ds_swizzle_b32 v5, v4 offset:swizzle(SWAP,16)
	v_cvt_pk_bf16_f32 v1, v6, v7
	v_cvt_pk_bf16_f32 v2, v2, v3
	v_cvt_pk_bf16_f32 v3, v8, v9
	global_store_dwordx4 v[22:23], v[0:3], off offset:256
	s_waitcnt lgkmcnt(0)
	s_nop 0
	v_add_f32_e32 v0, v4, v5
	v_mov_b32_e32 v1, v0
	s_nop 1
	v_permlane32_swap_b32_e32 v0, v1
	s_and_saveexec_b64 s[26:27], s[2:3]
	s_cbranch_execz .LBB0_520
	v_add_f32_e32 v2, v0, v1
	v_lshlrev_b64 v[0:1], 6, v[16:17]
	v_lshl_add_u64 v[0:1], s[10:11], 0, v[0:1]
	v_lshl_add_u64 v[0:1], s[24:25], 2, v[0:1]
	s_lshl_b32 s6, s38, 2
	v_lshl_add_u64 v[0:1], v[0:1], 0, s[6:7]
	global_store_dword v[0:1], v2, off
